# P0 x-row pass rewritten: 4 rows per wave in one pass so each LDS dt-weight read feeds 4 rows, deep ds_read pipeline, one softplus pass (f32 math unchanged)
# speedup vs baseline: 1.0110x; 1.0054x over previous
.LBB0_195:
	global_load_dword v24, v[0:1], off
	global_load_dwordx4 v[8:11], v[2:3], off
	global_load_dwordx4 v[12:15], v[2:3], off offset:16
	global_load_dwordx4 v[16:19], v[2:3], off offset:32
	global_load_dwordx4 v[20:23], v[2:3], off offset:48
	v_and_b32_e32 v7, 0xc0, v5
	v_and_b32_e32 v25, 0x700, v6
	v_or3_b32 v7, v25, v7, v4
	v_and_b32_e32 v26, 48, v6
	v_lshl_add_u32 v7, v7, 6, 0
	v_add_u32_e32 v27, 0x200, v6
	v_cmp_lt_u32_e32 vcc, s6, v6
	v_add_u32_e32 v25, v7, v26
	v_lshl_add_u64 v[0:1], v[0:1], 0, s[2:3]
	v_lshl_add_u64 v[2:3], v[2:3], 0, s[4:5]
	v_add_u32_e32 v5, 0x8000, v5
	s_or_b64 s[0:1], vcc, s[0:1]
	v_mov_b32_e32 v6, v27
	v_xad_u32 v27, v26, 16, v7
	v_xad_u32 v28, v26, 32, v7
	v_xad_u32 v7, v26, 48, v7
	s_waitcnt vmcnt(3)
	v_pk_mul_f32 v[10:11], v[10:11], v[24:25] op_sel_hi:[1,0]
	v_pk_mul_f32 v[8:9], v[8:9], v[24:25] op_sel_hi:[1,0]
	s_waitcnt vmcnt(2)
	v_pk_mul_f32 v[14:15], v[24:25], v[14:15] op_sel_hi:[0,1]
	v_pk_mul_f32 v[12:13], v[24:25], v[12:13] op_sel_hi:[0,1]
	s_waitcnt vmcnt(1)
	v_pk_mul_f32 v[18:19], v[24:25], v[18:19] op_sel_hi:[0,1]
	v_pk_mul_f32 v[16:17], v[24:25], v[16:17] op_sel_hi:[0,1]
	s_waitcnt vmcnt(0)
	v_pk_mul_f32 v[22:23], v[24:25], v[22:23] op_sel_hi:[0,1]
	v_pk_mul_f32 v[20:21], v[24:25], v[20:21] op_sel_hi:[0,1]
	ds_write_b128 v25, v[8:11]
	ds_write_b128 v27, v[12:15]
	ds_write_b128 v28, v[16:19]
	ds_write_b128 v7, v[20:23]
	s_andn2_b64 exec, exec, s[0:1]
	s_cbranch_execnz .LBB0_195
	s_or_b64 exec, exec, s[0:1]
	s_movk_i32 s0, 0x2000
	v_cmp_gt_i32_e32 vcc, s0, v64
	v_ashrrev_i32_e32 v65, 31, v64
	s_waitcnt lgkmcnt(0)
	s_barrier
	s_and_saveexec_b64 s[14:15], vcc
	s_cbranch_execz .LBB0_205
	v_mbcnt_lo_u32_b32 v0, -1, 0
	v_mbcnt_hi_u32_b32 v0, -1, v0
	v_and_b32_e32 v1, 64, v0
	v_add_u32_e32 v1, 64, v1
	v_xor_b32_e32 v2, 1, v0
	v_cmp_lt_i32_e32 vcc, v2, v1
	v_readlane_b32 s16, v252, 7
	v_readlane_b32 s20, v252, 11
	v_cndmask_b32_e32 v2, v0, v2, vcc
	v_lshlrev_b32_e32 v48, 2, v2
	v_xor_b32_e32 v2, 2, v0
	v_cmp_lt_i32_e32 vcc, v2, v1
	v_readlane_b32 s21, v252, 12
	v_bitop3_b32 v4, v158, 4, 12 bitop3:0x6c
	v_cndmask_b32_e32 v2, v0, v2, vcc
	v_lshlrev_b32_e32 v49, 2, v2
	v_xor_b32_e32 v2, 4, v0
	v_cmp_lt_i32_e32 vcc, v2, v1
	v_bitop3_b32 v5, v158, 8, 12 bitop3:0x6c
	v_bitop3_b32 v6, v158, 12, v158 bitop3:0xc
	v_cndmask_b32_e32 v2, v0, v2, vcc
	v_lshlrev_b32_e32 v50, 2, v2
	v_xor_b32_e32 v2, 8, v0
	v_cmp_lt_i32_e32 vcc, v2, v1
	v_lshlrev_b32_e32 v4, 2, v4
	v_lshlrev_b32_e32 v5, 2, v5
	v_cndmask_b32_e32 v2, v0, v2, vcc
	v_lshlrev_b32_e32 v51, 2, v2
	v_xor_b32_e32 v2, 16, v0
	v_cmp_lt_i32_e32 vcc, v2, v1
	v_lshlrev_b32_e32 v6, 2, v6
	s_add_i32 s10, 0, 0x10000
	v_cndmask_b32_e32 v2, v0, v2, vcc
	v_lshlrev_b32_e32 v52, 2, v2
	v_xor_b32_e32 v2, 32, v0
	v_cmp_lt_i32_e32 vcc, v2, v1
	v_mov_b32_e32 v1, 0
	v_readlane_b32 s17, v252, 8
	v_cndmask_b32_e32 v0, v0, v2, vcc
	v_lshlrev_b32_e32 v53, 2, v0
	v_and_b32_e32 v0, 32, v158
	v_cmp_eq_u32_e32 vcc, 0, v0
	v_and_b32_e32 v0, 16, v158
	v_cmp_eq_u32_e64 s[0:1], 0, v0
	v_and_b32_e32 v0, 8, v158
	v_cmp_eq_u32_e64 s[2:3], 0, v0
	v_and_b32_e32 v0, 4, v158
	v_cmp_eq_u32_e64 s[4:5], 0, v0
	v_and_b32_e32 v0, 3, v158
	v_cmp_eq_u32_e64 s[6:7], 0, v0
	v_and_b32_e32 v0, 60, v93
	v_and_b32_e32 v2, 12, v158
	v_lshl_add_u64 v[32:33], s[20:21], 0, v[0:1]
	v_lshlrev_b32_e32 v1, 6, v93
	v_add_u32_e32 v3, 0, v1
	v_lshlrev_b32_e32 v2, 2, v2
	v_add_u32_e32 v54, v3, v2
	v_add_u32_e32 v55, v3, v4
	v_add_u32_e32 v56, v3, v5
	v_add_u32_e32 v57, v3, v6
	v_add_u32_e32 v3, s10, v1
	s_add_i32 s10, 0, 0x11000
	v_add_u32_e32 v58, v3, v2
	v_add_u32_e32 v59, v3, v4
	v_add_u32_e32 v60, v3, v5
	v_add_u32_e32 v61, v3, v6
	v_add_u32_e32 v3, s10, v1
	s_add_i32 s10, 0, 0x12000
	v_add_u32_e32 v62, v3, v2
	v_add_u32_e32 v63, v3, v4
	v_add_u32_e32 v66, v3, v5
	v_add_u32_e32 v67, v3, v6
	v_add_u32_e32 v3, s10, v1
	s_add_i32 s10, 0, 0x13000
	v_add_u32_e32 v68, v3, v2
	v_add_u32_e32 v69, v3, v4
	v_add_u32_e32 v70, v3, v5
	v_add_u32_e32 v71, v3, v6
	v_add_u32_e32 v3, s10, v1
	s_add_i32 s10, 0, 0x14000
	v_add_u32_e32 v72, v3, v2
	v_add_u32_e32 v73, v3, v4
	v_add_u32_e32 v74, v3, v5
	v_add_u32_e32 v75, v3, v6
	v_add_u32_e32 v3, s10, v1
	s_add_i32 s10, 0, 0x15000
	v_add_u32_e32 v76, v3, v2
	v_add_u32_e32 v77, v3, v4
	v_add_u32_e32 v78, v3, v5
	v_add_u32_e32 v79, v3, v6
	v_add_u32_e32 v3, s10, v1
	s_add_i32 s10, 0, 0x16000
	v_add_u32_e32 v80, v3, v2
	v_add_u32_e32 v81, v3, v4
	v_add_u32_e32 v82, v3, v5
	v_add_u32_e32 v83, v3, v6
	v_add_u32_e32 v3, s10, v1
	s_add_i32 s10, 0, 0x17000
	v_add_u32_e32 v84, v3, v2
	v_add_u32_e32 v85, v3, v4
	v_add_u32_e32 v86, v3, v5
	v_add_u32_e32 v87, v3, v6
	v_add_u32_e32 v3, s10, v1
	s_add_i32 s10, 0, 0x18000
	v_add_u32_e32 v88, v3, v2
	v_add_u32_e32 v89, v3, v4
	v_add_u32_e32 v90, v3, v5
	v_add_u32_e32 v91, v3, v6
	v_add_u32_e32 v3, s10, v1
	s_add_i32 s10, 0, 0x19000
	v_add_u32_e32 v92, v3, v2
	v_add_u32_e32 v94, v3, v4
	v_add_u32_e32 v95, v3, v5
	v_add_u32_e32 v96, v3, v6
	v_add_u32_e32 v3, s10, v1
	s_add_i32 s10, 0, 0x1a000
	v_add_u32_e32 v97, v3, v2
	v_add_u32_e32 v98, v3, v4
	v_add_u32_e32 v99, v3, v5
	v_add_u32_e32 v100, v3, v6
	v_add_u32_e32 v3, s10, v1
	s_add_i32 s10, 0, 0x1b000
	v_add_u32_e32 v101, v3, v2
	v_add_u32_e32 v102, v3, v4
	v_add_u32_e32 v103, v3, v5
	v_add_u32_e32 v104, v3, v6
	v_add_u32_e32 v3, s10, v1
	s_add_i32 s10, 0, 0x1c000
	v_add_u32_e32 v105, v3, v2
	v_add_u32_e32 v106, v3, v4
	v_add_u32_e32 v107, v3, v5
	v_add_u32_e32 v108, v3, v6
	v_add_u32_e32 v3, s10, v1
	s_add_i32 s10, 0, 0x1d000
	v_add_u32_e32 v109, v3, v2
	v_add_u32_e32 v110, v3, v4
	v_add_u32_e32 v111, v3, v5
	v_add_u32_e32 v112, v3, v6
	v_add_u32_e32 v3, s10, v1
	s_add_i32 s10, 0, 0x1e000
	v_add_u32_e32 v113, v3, v2
	v_add_u32_e32 v114, v3, v4
	v_add_u32_e32 v115, v3, v5
	v_add_u32_e32 v116, v3, v6
	v_add_u32_e32 v3, s10, v1
	s_add_i32 s10, 0, 0x1f000
	v_add_u32_e32 v1, s10, v1
	v_add_u32_e32 v117, v3, v2
	v_add_u32_e32 v118, v3, v4
	v_add_u32_e32 v119, v3, v5
	v_add_u32_e32 v120, v3, v6
	v_add_u32_e32 v121, v1, v2
	v_mov_b64_e32 v[2:3], 0x5080000
	v_lshl_add_u64 v[34:35], v[64:65], 2, v[2:3]
	v_lshlrev_b64 v[2:3], 6, v[64:65]
	v_add_u32_e32 v122, v1, v4
	v_add_u32_e32 v123, v1, v5
	v_add_u32_e32 v124, v1, v6
	v_or_b32_e32 v2, v2, v0
	v_lshlrev_b64 v[0:1], 13, v[64:65]
	s_mov_b64 s[10:11], 0x5000000
	v_lshl_or_b32 v0, v93, 4, v0
	v_readlane_b32 s18, v252, 9
	v_readlane_b32 s19, v252, 10
	v_readlane_b32 s22, v252, 13
	v_readlane_b32 s23, v252, 14
	v_readlane_b32 s24, v252, 15
	v_readlane_b32 s25, v252, 16
	v_readlane_b32 s30, v252, 21
	v_readlane_b32 s31, v252, 22
	s_ashr_i32 s13, s12, 31
	v_lshl_add_u64 v[36:37], v[2:3], 0, s[10:11]
	v_lshl_add_u64 v[0:1], s[48:49], 0, v[0:1]
	s_mov_b64 s[10:11], 0x1000
	v_lshlrev_b64 v[40:41], 12, v[64:65]
	v_cmp_eq_u32_e64 s[8:9], 0, v93
	s_lshl_b64 s[16:17], s[12:13], 2
	s_lshl_b64 s[18:19], s[12:13], 6
	v_lshl_add_u64 v[38:39], v[0:1], 0, s[10:11]
	s_lshl_b64 s[20:21], s[12:13], 13
	v_lshl_or_b32 v40, v93, 3, v40
	s_lshl_b64 s[22:23], s[12:13], 12
	s_mov_b64 s[24:25], 0
	v_mov_b32_e32 v125, 0x358637bd
	s_mov_b32 s13, 0x800000
	s_mov_b32 s30, 0x7400000
	s_mov_b32 s31, 0x41a00000
	s_mov_b32 s34, 0x3fb8aa3b
	s_mov_b32 s35, 0xc2ce8ed0
	s_mov_b32 s36, 0x42b17218
	s_mov_b32 s37, 0x7f800000
	s_mov_b32 s38, 0x3f2aaaab
	v_mov_b32_e32 v126, 0x3ecc95a3
	s_mov_b32 s39, 0x3f317218
	s_mov_b32 s40, 0x33800000
	s_movk_i32 s41, 0x1fff
	v_mov_b32_e32 v127, 0x7f800000
	v_mov_b32_e32 v42, 0x3f317218
	v_mov_b32_e32 v128, v64
	v_readlane_b32 s26, v252, 17
	v_readlane_b32 s27, v252, 18
	v_readlane_b32 s28, v252, 19
	v_readlane_b32 s29, v252, 20
	s_cmp_eq_u32 s12, 0x800
	s_cbranch_scc1 .Lmy_partb4
	s_branch .LBB0_199

.Lmy_partb4:
	s_waitcnt lgkmcnt(0)
	global_load_dword v253, v[32:33], off
	v_lshl_add_u64 v[8:9], v[38:39], 0, s[20:21]
	v_lshl_add_u64 v[10:11], v[8:9], 0, s[20:21]
	v_lshl_add_u64 v[12:13], v[10:11], 0, s[20:21]
	global_load_dwordx4 v[160:163], v[38:39], off offset:-4096 nt
	global_load_dwordx4 v[164:167], v[8:9], off offset:-4096 nt
	global_load_dwordx4 v[168:171], v[10:11], off offset:-4096 nt
	global_load_dwordx4 v[172:175], v[12:13], off offset:-4096 nt
	global_load_dwordx4 v[176:179], v[38:39], off offset:-3072 nt
	global_load_dwordx4 v[180:183], v[8:9], off offset:-3072 nt
	global_load_dwordx4 v[184:187], v[10:11], off offset:-3072 nt
	global_load_dwordx4 v[188:191], v[12:13], off offset:-3072 nt
	global_load_dwordx4 v[192:195], v[38:39], off offset:-2048 nt
	global_load_dwordx4 v[196:199], v[8:9], off offset:-2048 nt
	global_load_dwordx4 v[200:203], v[10:11], off offset:-2048 nt
	global_load_dwordx4 v[204:207], v[12:13], off offset:-2048 nt
	global_load_dwordx4 v[208:211], v[38:39], off offset:-1024 nt
	global_load_dwordx4 v[212:215], v[8:9], off offset:-1024 nt
	global_load_dwordx4 v[216:219], v[10:11], off offset:-1024 nt
	global_load_dwordx4 v[220:223], v[12:13], off offset:-1024 nt
	global_load_dwordx4 v[224:227], v[38:39], off nt
	global_load_dwordx4 v[228:231], v[8:9], off nt
	global_load_dwordx4 v[0:3], v[10:11], off nt
	global_load_dwordx4 v[4:7], v[12:13], off nt
	v_lshl_add_u64 v[14:15], s[84:85], 0, v[40:41]
	v_add_co_u32_e64 v14, s[10:11], s30, v14
	s_nop 1
	v_addc_co_u32_e64 v15, s[10:11], 0, v15, s[10:11]
	v_lshl_add_u64 v[16:17], v[14:15], 0, s[22:23]
	v_lshl_add_u64 v[18:19], v[16:17], 0, s[22:23]
	v_lshl_add_u64 v[20:21], v[18:19], 0, s[22:23]
	v_mov_b32_e32 v240, 0
	v_mov_b32_e32 v241, 0
	v_mov_b32_e32 v242, 0
	v_mov_b32_e32 v243, 0
	v_mov_b32_e32 v66, 0
	v_mov_b32_e32 v67, 0
	v_mov_b32_e32 v68, 0
	v_mov_b32_e32 v69, 0
	v_mov_b32_e32 v70, 0
	v_mov_b32_e32 v71, 0
	v_mov_b32_e32 v72, 0
	v_mov_b32_e32 v73, 0
	v_mov_b32_e32 v74, 0
	v_mov_b32_e32 v75, 0
	v_mov_b32_e32 v76, 0
	v_mov_b32_e32 v77, 0
	v_mov_b32_e32 v78, 0
	v_mov_b32_e32 v79, 0
	v_mov_b32_e32 v80, 0
	v_mov_b32_e32 v81, 0
	v_mov_b32_e32 v82, 0
	v_mov_b32_e32 v83, 0
	v_mov_b32_e32 v84, 0
	v_mov_b32_e32 v85, 0
	v_mov_b32_e32 v86, 0
	v_mov_b32_e32 v87, 0
	v_mov_b32_e32 v88, 0
	v_mov_b32_e32 v89, 0
	v_mov_b32_e32 v90, 0
	v_mov_b32_e32 v91, 0
	v_mov_b32_e32 v94, 0
	v_mov_b32_e32 v95, 0
	v_mov_b32_e32 v96, 0
	v_mov_b32_e32 v97, 0
	v_mov_b32_e32 v98, 0
	v_mov_b32_e32 v99, 0
	v_mov_b32_e32 v100, 0
	v_mov_b32_e32 v101, 0
	v_mov_b32_e32 v102, 0
	v_mov_b32_e32 v103, 0
	v_mov_b32_e32 v104, 0
	v_mov_b32_e32 v105, 0
	v_mov_b32_e32 v106, 0
	v_mov_b32_e32 v107, 0
	v_mov_b32_e32 v108, 0
	v_mov_b32_e32 v109, 0
	v_mov_b32_e32 v110, 0
	v_mov_b32_e32 v111, 0
	v_mov_b32_e32 v112, 0
	v_mov_b32_e32 v113, 0
	v_mov_b32_e32 v114, 0
	v_mov_b32_e32 v115, 0
	v_mov_b32_e32 v116, 0
	v_mov_b32_e32 v117, 0
	v_mov_b32_e32 v118, 0
	v_mov_b32_e32 v119, 0
	v_mov_b32_e32 v120, 0
	v_mov_b32_e32 v121, 0
	v_mov_b32_e32 v122, 0
	v_mov_b32_e32 v123, 0
	v_mov_b32_e32 v24, 0
	v_mov_b32_e32 v25, 0
	v_mov_b32_e32 v26, 0
	v_mov_b32_e32 v27, 0
	v_mov_b32_e32 v28, 0
	v_mov_b32_e32 v29, 0
	v_mov_b32_e32 v30, 0
	v_mov_b32_e32 v31, 0
	ds_read_b128 v[130:133], v54
	ds_read_b128 v[134:137], v55
	ds_read_b128 v[138:141], v56
	ds_read_b128 v[142:145], v57
	ds_read_b128 v[146:149], v54 offset:4096
	ds_read_b128 v[150:153], v55 offset:4096
	ds_read_b128 v[154:157], v56 offset:4096
	ds_read_b128 v[44:47], v57 offset:4096
	s_waitcnt vmcnt(19)
	v_cvt_pk_bf16_f32 v244, v160, v161
	v_cvt_pk_bf16_f32 v245, v162, v163
	global_store_dwordx2 v[14:15], v[244:245], off
	v_pk_mul_f32 v[22:23], v[160:161], v[160:161]
	v_pk_fma_f32 v[22:23], v[162:163], v[162:163], v[22:23]
	v_add_f32_e32 v22, v22, v23
	v_add_f32_e32 v240, v240, v22
	s_waitcnt vmcnt(19)
	v_cvt_pk_bf16_f32 v246, v164, v165
	v_cvt_pk_bf16_f32 v247, v166, v167
	global_store_dwordx2 v[16:17], v[246:247], off
	v_pk_mul_f32 v[22:23], v[164:165], v[164:165]
	v_pk_fma_f32 v[22:23], v[166:167], v[166:167], v[22:23]
	v_add_f32_e32 v22, v22, v23
	v_add_f32_e32 v241, v241, v22
	s_waitcnt vmcnt(19)
	v_cvt_pk_bf16_f32 v248, v168, v169
	v_cvt_pk_bf16_f32 v249, v170, v171
	global_store_dwordx2 v[18:19], v[248:249], off
	v_pk_mul_f32 v[22:23], v[168:169], v[168:169]
	v_pk_fma_f32 v[22:23], v[170:171], v[170:171], v[22:23]
	v_add_f32_e32 v22, v22, v23
	v_add_f32_e32 v242, v242, v22
	s_waitcnt vmcnt(19)
	v_cvt_pk_bf16_f32 v232, v172, v173
	v_cvt_pk_bf16_f32 v233, v174, v175
	global_store_dwordx2 v[20:21], v[232:233], off
	v_pk_mul_f32 v[22:23], v[172:173], v[172:173]
	v_pk_fma_f32 v[22:23], v[174:175], v[174:175], v[22:23]
	v_add_f32_e32 v22, v22, v23
	v_add_f32_e32 v243, v243, v22
	s_waitcnt lgkmcnt(7)
	v_pk_fma_f32 v[66:67], v[160:161], v[130:131], v[66:67] op_sel_hi:[0,1,1]
	v_pk_fma_f32 v[82:83], v[164:165], v[130:131], v[82:83] op_sel_hi:[0,1,1]
	v_pk_fma_f32 v[100:101], v[168:169], v[130:131], v[100:101] op_sel_hi:[0,1,1]
	v_pk_fma_f32 v[116:117], v[172:173], v[130:131], v[116:117] op_sel_hi:[0,1,1]
	v_pk_fma_f32 v[68:69], v[160:161], v[132:133], v[68:69] op_sel_hi:[0,1,1]
	v_pk_fma_f32 v[84:85], v[164:165], v[132:133], v[84:85] op_sel_hi:[0,1,1]
	v_pk_fma_f32 v[102:103], v[168:169], v[132:133], v[102:103] op_sel_hi:[0,1,1]
	v_pk_fma_f32 v[118:119], v[172:173], v[132:133], v[118:119] op_sel_hi:[0,1,1]
	ds_read_b128 v[130:133], v54 offset:8192
	s_waitcnt lgkmcnt(7)
	v_pk_fma_f32 v[70:71], v[160:161], v[134:135], v[70:71] op_sel_hi:[0,1,1]
	v_pk_fma_f32 v[86:87], v[164:165], v[134:135], v[86:87] op_sel_hi:[0,1,1]
	v_pk_fma_f32 v[104:105], v[168:169], v[134:135], v[104:105] op_sel_hi:[0,1,1]
	v_pk_fma_f32 v[120:121], v[172:173], v[134:135], v[120:121] op_sel_hi:[0,1,1]
	v_pk_fma_f32 v[72:73], v[160:161], v[136:137], v[72:73] op_sel_hi:[0,1,1]
	v_pk_fma_f32 v[88:89], v[164:165], v[136:137], v[88:89] op_sel_hi:[0,1,1]
	v_pk_fma_f32 v[106:107], v[168:169], v[136:137], v[106:107] op_sel_hi:[0,1,1]
	v_pk_fma_f32 v[122:123], v[172:173], v[136:137], v[122:123] op_sel_hi:[0,1,1]
	ds_read_b128 v[134:137], v55 offset:8192
	s_waitcnt lgkmcnt(7)
	v_pk_fma_f32 v[74:75], v[160:161], v[138:139], v[74:75] op_sel_hi:[0,1,1]
	v_pk_fma_f32 v[90:91], v[164:165], v[138:139], v[90:91] op_sel_hi:[0,1,1]
	v_pk_fma_f32 v[108:109], v[168:169], v[138:139], v[108:109] op_sel_hi:[0,1,1]
	v_pk_fma_f32 v[24:25], v[172:173], v[138:139], v[24:25] op_sel_hi:[0,1,1]
	v_pk_fma_f32 v[76:77], v[160:161], v[140:141], v[76:77] op_sel_hi:[0,1,1]
	v_pk_fma_f32 v[94:95], v[164:165], v[140:141], v[94:95] op_sel_hi:[0,1,1]
	v_pk_fma_f32 v[110:111], v[168:169], v[140:141], v[110:111] op_sel_hi:[0,1,1]
	v_pk_fma_f32 v[26:27], v[172:173], v[140:141], v[26:27] op_sel_hi:[0,1,1]
	ds_read_b128 v[138:141], v56 offset:8192
	s_waitcnt lgkmcnt(7)
	v_pk_fma_f32 v[78:79], v[160:161], v[142:143], v[78:79] op_sel_hi:[0,1,1]
	v_pk_fma_f32 v[96:97], v[164:165], v[142:143], v[96:97] op_sel_hi:[0,1,1]
	v_pk_fma_f32 v[112:113], v[168:169], v[142:143], v[112:113] op_sel_hi:[0,1,1]
	v_pk_fma_f32 v[28:29], v[172:173], v[142:143], v[28:29] op_sel_hi:[0,1,1]
	v_pk_fma_f32 v[80:81], v[160:161], v[144:145], v[80:81] op_sel_hi:[0,1,1]
	v_pk_fma_f32 v[98:99], v[164:165], v[144:145], v[98:99] op_sel_hi:[0,1,1]
	v_pk_fma_f32 v[114:115], v[168:169], v[144:145], v[114:115] op_sel_hi:[0,1,1]
	v_pk_fma_f32 v[30:31], v[172:173], v[144:145], v[30:31] op_sel_hi:[0,1,1]
	ds_read_b128 v[142:145], v57 offset:8192
	s_waitcnt lgkmcnt(7)
	v_pk_fma_f32 v[66:67], v[160:161], v[146:147], v[66:67] op_sel:[1,0,0]
	v_pk_fma_f32 v[82:83], v[164:165], v[146:147], v[82:83] op_sel:[1,0,0]
	v_pk_fma_f32 v[100:101], v[168:169], v[146:147], v[100:101] op_sel:[1,0,0]
	v_pk_fma_f32 v[116:117], v[172:173], v[146:147], v[116:117] op_sel:[1,0,0]
	v_pk_fma_f32 v[68:69], v[160:161], v[148:149], v[68:69] op_sel:[1,0,0]
	v_pk_fma_f32 v[84:85], v[164:165], v[148:149], v[84:85] op_sel:[1,0,0]
	v_pk_fma_f32 v[102:103], v[168:169], v[148:149], v[102:103] op_sel:[1,0,0]
	v_pk_fma_f32 v[118:119], v[172:173], v[148:149], v[118:119] op_sel:[1,0,0]
	ds_read_b128 v[146:149], v54 offset:12288
	s_waitcnt lgkmcnt(7)
	v_pk_fma_f32 v[70:71], v[160:161], v[150:151], v[70:71] op_sel:[1,0,0]
	v_pk_fma_f32 v[86:87], v[164:165], v[150:151], v[86:87] op_sel:[1,0,0]
	v_pk_fma_f32 v[104:105], v[168:169], v[150:151], v[104:105] op_sel:[1,0,0]
	v_pk_fma_f32 v[120:121], v[172:173], v[150:151], v[120:121] op_sel:[1,0,0]
	v_pk_fma_f32 v[72:73], v[160:161], v[152:153], v[72:73] op_sel:[1,0,0]
	v_pk_fma_f32 v[88:89], v[164:165], v[152:153], v[88:89] op_sel:[1,0,0]
	v_pk_fma_f32 v[106:107], v[168:169], v[152:153], v[106:107] op_sel:[1,0,0]
	v_pk_fma_f32 v[122:123], v[172:173], v[152:153], v[122:123] op_sel:[1,0,0]
	ds_read_b128 v[150:153], v55 offset:12288
	s_waitcnt lgkmcnt(7)
	v_pk_fma_f32 v[74:75], v[160:161], v[154:155], v[74:75] op_sel:[1,0,0]
	v_pk_fma_f32 v[90:91], v[164:165], v[154:155], v[90:91] op_sel:[1,0,0]
	v_pk_fma_f32 v[108:109], v[168:169], v[154:155], v[108:109] op_sel:[1,0,0]
	v_pk_fma_f32 v[24:25], v[172:173], v[154:155], v[24:25] op_sel:[1,0,0]
	v_pk_fma_f32 v[76:77], v[160:161], v[156:157], v[76:77] op_sel:[1,0,0]
	v_pk_fma_f32 v[94:95], v[164:165], v[156:157], v[94:95] op_sel:[1,0,0]
	v_pk_fma_f32 v[110:111], v[168:169], v[156:157], v[110:111] op_sel:[1,0,0]
	v_pk_fma_f32 v[26:27], v[172:173], v[156:157], v[26:27] op_sel:[1,0,0]
	ds_read_b128 v[154:157], v56 offset:12288
	s_waitcnt lgkmcnt(7)
	v_pk_fma_f32 v[78:79], v[160:161], v[44:45], v[78:79] op_sel:[1,0,0]
	v_pk_fma_f32 v[96:97], v[164:165], v[44:45], v[96:97] op_sel:[1,0,0]
	v_pk_fma_f32 v[112:113], v[168:169], v[44:45], v[112:113] op_sel:[1,0,0]
	v_pk_fma_f32 v[28:29], v[172:173], v[44:45], v[28:29] op_sel:[1,0,0]
	v_pk_fma_f32 v[80:81], v[160:161], v[46:47], v[80:81] op_sel:[1,0,0]
	v_pk_fma_f32 v[98:99], v[164:165], v[46:47], v[98:99] op_sel:[1,0,0]
	v_pk_fma_f32 v[114:115], v[168:169], v[46:47], v[114:115] op_sel:[1,0,0]
	v_pk_fma_f32 v[30:31], v[172:173], v[46:47], v[30:31] op_sel:[1,0,0]
	ds_read_b128 v[44:47], v57 offset:12288
	s_waitcnt lgkmcnt(7)
	v_pk_fma_f32 v[66:67], v[162:163], v[130:131], v[66:67] op_sel_hi:[0,1,1]
	v_pk_fma_f32 v[82:83], v[166:167], v[130:131], v[82:83] op_sel_hi:[0,1,1]
	v_pk_fma_f32 v[100:101], v[170:171], v[130:131], v[100:101] op_sel_hi:[0,1,1]
	v_pk_fma_f32 v[116:117], v[174:175], v[130:131], v[116:117] op_sel_hi:[0,1,1]
	v_pk_fma_f32 v[68:69], v[162:163], v[132:133], v[68:69] op_sel_hi:[0,1,1]
	v_pk_fma_f32 v[84:85], v[166:167], v[132:133], v[84:85] op_sel_hi:[0,1,1]
	v_pk_fma_f32 v[102:103], v[170:171], v[132:133], v[102:103] op_sel_hi:[0,1,1]
	v_pk_fma_f32 v[118:119], v[174:175], v[132:133], v[118:119] op_sel_hi:[0,1,1]
	ds_read_b128 v[130:133], v54 offset:16384
	s_waitcnt lgkmcnt(7)
	v_pk_fma_f32 v[70:71], v[162:163], v[134:135], v[70:71] op_sel_hi:[0,1,1]
	v_pk_fma_f32 v[86:87], v[166:167], v[134:135], v[86:87] op_sel_hi:[0,1,1]
	v_pk_fma_f32 v[104:105], v[170:171], v[134:135], v[104:105] op_sel_hi:[0,1,1]
	v_pk_fma_f32 v[120:121], v[174:175], v[134:135], v[120:121] op_sel_hi:[0,1,1]
	v_pk_fma_f32 v[72:73], v[162:163], v[136:137], v[72:73] op_sel_hi:[0,1,1]
	v_pk_fma_f32 v[88:89], v[166:167], v[136:137], v[88:89] op_sel_hi:[0,1,1]
	v_pk_fma_f32 v[106:107], v[170:171], v[136:137], v[106:107] op_sel_hi:[0,1,1]
	v_pk_fma_f32 v[122:123], v[174:175], v[136:137], v[122:123] op_sel_hi:[0,1,1]
	ds_read_b128 v[134:137], v55 offset:16384
	s_waitcnt lgkmcnt(7)
	v_pk_fma_f32 v[74:75], v[162:163], v[138:139], v[74:75] op_sel_hi:[0,1,1]
	v_pk_fma_f32 v[90:91], v[166:167], v[138:139], v[90:91] op_sel_hi:[0,1,1]
	v_pk_fma_f32 v[108:109], v[170:171], v[138:139], v[108:109] op_sel_hi:[0,1,1]
	v_pk_fma_f32 v[24:25], v[174:175], v[138:139], v[24:25] op_sel_hi:[0,1,1]
	v_pk_fma_f32 v[76:77], v[162:163], v[140:141], v[76:77] op_sel_hi:[0,1,1]
	v_pk_fma_f32 v[94:95], v[166:167], v[140:141], v[94:95] op_sel_hi:[0,1,1]
	v_pk_fma_f32 v[110:111], v[170:171], v[140:141], v[110:111] op_sel_hi:[0,1,1]
	v_pk_fma_f32 v[26:27], v[174:175], v[140:141], v[26:27] op_sel_hi:[0,1,1]
	ds_read_b128 v[138:141], v56 offset:16384
	s_waitcnt lgkmcnt(7)
	v_pk_fma_f32 v[78:79], v[162:163], v[142:143], v[78:79] op_sel_hi:[0,1,1]
	v_pk_fma_f32 v[96:97], v[166:167], v[142:143], v[96:97] op_sel_hi:[0,1,1]
	v_pk_fma_f32 v[112:113], v[170:171], v[142:143], v[112:113] op_sel_hi:[0,1,1]
	v_pk_fma_f32 v[28:29], v[174:175], v[142:143], v[28:29] op_sel_hi:[0,1,1]
	v_pk_fma_f32 v[80:81], v[162:163], v[144:145], v[80:81] op_sel_hi:[0,1,1]
	v_pk_fma_f32 v[98:99], v[166:167], v[144:145], v[98:99] op_sel_hi:[0,1,1]
	v_pk_fma_f32 v[114:115], v[170:171], v[144:145], v[114:115] op_sel_hi:[0,1,1]
	v_pk_fma_f32 v[30:31], v[174:175], v[144:145], v[30:31] op_sel_hi:[0,1,1]
	ds_read_b128 v[142:145], v57 offset:16384
	s_waitcnt lgkmcnt(7)
	v_pk_fma_f32 v[66:67], v[162:163], v[146:147], v[66:67] op_sel:[1,0,0]
	v_pk_fma_f32 v[82:83], v[166:167], v[146:147], v[82:83] op_sel:[1,0,0]
	v_pk_fma_f32 v[100:101], v[170:171], v[146:147], v[100:101] op_sel:[1,0,0]
	v_pk_fma_f32 v[116:117], v[174:175], v[146:147], v[116:117] op_sel:[1,0,0]
	v_pk_fma_f32 v[68:69], v[162:163], v[148:149], v[68:69] op_sel:[1,0,0]
	v_pk_fma_f32 v[84:85], v[166:167], v[148:149], v[84:85] op_sel:[1,0,0]
	v_pk_fma_f32 v[102:103], v[170:171], v[148:149], v[102:103] op_sel:[1,0,0]
	v_pk_fma_f32 v[118:119], v[174:175], v[148:149], v[118:119] op_sel:[1,0,0]
	ds_read_b128 v[146:149], v54 offset:20480
	s_waitcnt lgkmcnt(7)
	v_pk_fma_f32 v[70:71], v[162:163], v[150:151], v[70:71] op_sel:[1,0,0]
	v_pk_fma_f32 v[86:87], v[166:167], v[150:151], v[86:87] op_sel:[1,0,0]
	v_pk_fma_f32 v[104:105], v[170:171], v[150:151], v[104:105] op_sel:[1,0,0]
	v_pk_fma_f32 v[120:121], v[174:175], v[150:151], v[120:121] op_sel:[1,0,0]
	v_pk_fma_f32 v[72:73], v[162:163], v[152:153], v[72:73] op_sel:[1,0,0]
	v_pk_fma_f32 v[88:89], v[166:167], v[152:153], v[88:89] op_sel:[1,0,0]
	v_pk_fma_f32 v[106:107], v[170:171], v[152:153], v[106:107] op_sel:[1,0,0]
	v_pk_fma_f32 v[122:123], v[174:175], v[152:153], v[122:123] op_sel:[1,0,0]
	ds_read_b128 v[150:153], v55 offset:20480
	s_waitcnt lgkmcnt(7)
	v_pk_fma_f32 v[74:75], v[162:163], v[154:155], v[74:75] op_sel:[1,0,0]
	v_pk_fma_f32 v[90:91], v[166:167], v[154:155], v[90:91] op_sel:[1,0,0]
	v_pk_fma_f32 v[108:109], v[170:171], v[154:155], v[108:109] op_sel:[1,0,0]
	v_pk_fma_f32 v[24:25], v[174:175], v[154:155], v[24:25] op_sel:[1,0,0]
	v_pk_fma_f32 v[76:77], v[162:163], v[156:157], v[76:77] op_sel:[1,0,0]
	v_pk_fma_f32 v[94:95], v[166:167], v[156:157], v[94:95] op_sel:[1,0,0]
	v_pk_fma_f32 v[110:111], v[170:171], v[156:157], v[110:111] op_sel:[1,0,0]
	v_pk_fma_f32 v[26:27], v[174:175], v[156:157], v[26:27] op_sel:[1,0,0]
	ds_read_b128 v[154:157], v56 offset:20480
	s_waitcnt lgkmcnt(7)
	v_pk_fma_f32 v[78:79], v[162:163], v[44:45], v[78:79] op_sel:[1,0,0]
	v_pk_fma_f32 v[96:97], v[166:167], v[44:45], v[96:97] op_sel:[1,0,0]
	v_pk_fma_f32 v[112:113], v[170:171], v[44:45], v[112:113] op_sel:[1,0,0]
	v_pk_fma_f32 v[28:29], v[174:175], v[44:45], v[28:29] op_sel:[1,0,0]
	v_pk_fma_f32 v[80:81], v[162:163], v[46:47], v[80:81] op_sel:[1,0,0]
	v_pk_fma_f32 v[98:99], v[166:167], v[46:47], v[98:99] op_sel:[1,0,0]
	v_pk_fma_f32 v[114:115], v[170:171], v[46:47], v[114:115] op_sel:[1,0,0]
	v_pk_fma_f32 v[30:31], v[174:175], v[46:47], v[30:31] op_sel:[1,0,0]
	ds_read_b128 v[44:47], v57 offset:20480
	global_load_dwordx4 v[160:163], v[38:39], off offset:1024 nt
	global_load_dwordx4 v[164:167], v[8:9], off offset:1024 nt
	global_load_dwordx4 v[168:171], v[10:11], off offset:1024 nt
	global_load_dwordx4 v[172:175], v[12:13], off offset:1024 nt
	s_waitcnt vmcnt(23)
	v_cvt_pk_bf16_f32 v244, v176, v177
	v_cvt_pk_bf16_f32 v245, v178, v179
	global_store_dwordx2 v[14:15], v[244:245], off offset:512
	v_pk_mul_f32 v[22:23], v[176:177], v[176:177]
	v_pk_fma_f32 v[22:23], v[178:179], v[178:179], v[22:23]
	v_add_f32_e32 v22, v22, v23
	v_add_f32_e32 v240, v240, v22
	s_waitcnt vmcnt(23)
	v_cvt_pk_bf16_f32 v246, v180, v181
	v_cvt_pk_bf16_f32 v247, v182, v183
	global_store_dwordx2 v[16:17], v[246:247], off offset:512
	v_pk_mul_f32 v[22:23], v[180:181], v[180:181]
	v_pk_fma_f32 v[22:23], v[182:183], v[182:183], v[22:23]
	v_add_f32_e32 v22, v22, v23
	v_add_f32_e32 v241, v241, v22
	s_waitcnt vmcnt(23)
	v_cvt_pk_bf16_f32 v248, v184, v185
	v_cvt_pk_bf16_f32 v249, v186, v187
	global_store_dwordx2 v[18:19], v[248:249], off offset:512
	v_pk_mul_f32 v[22:23], v[184:185], v[184:185]
	v_pk_fma_f32 v[22:23], v[186:187], v[186:187], v[22:23]
	v_add_f32_e32 v22, v22, v23
	v_add_f32_e32 v242, v242, v22
	s_waitcnt vmcnt(23)
	v_cvt_pk_bf16_f32 v232, v188, v189
	v_cvt_pk_bf16_f32 v233, v190, v191
	global_store_dwordx2 v[20:21], v[232:233], off offset:512
	v_pk_mul_f32 v[22:23], v[188:189], v[188:189]
	v_pk_fma_f32 v[22:23], v[190:191], v[190:191], v[22:23]
	v_add_f32_e32 v22, v22, v23
	v_add_f32_e32 v243, v243, v22
	s_waitcnt lgkmcnt(7)
	v_pk_fma_f32 v[66:67], v[176:177], v[130:131], v[66:67] op_sel_hi:[0,1,1]
	v_pk_fma_f32 v[82:83], v[180:181], v[130:131], v[82:83] op_sel_hi:[0,1,1]
	v_pk_fma_f32 v[100:101], v[184:185], v[130:131], v[100:101] op_sel_hi:[0,1,1]
	v_pk_fma_f32 v[116:117], v[188:189], v[130:131], v[116:117] op_sel_hi:[0,1,1]
	v_pk_fma_f32 v[68:69], v[176:177], v[132:133], v[68:69] op_sel_hi:[0,1,1]
	v_pk_fma_f32 v[84:85], v[180:181], v[132:133], v[84:85] op_sel_hi:[0,1,1]
	v_pk_fma_f32 v[102:103], v[184:185], v[132:133], v[102:103] op_sel_hi:[0,1,1]
	v_pk_fma_f32 v[118:119], v[188:189], v[132:133], v[118:119] op_sel_hi:[0,1,1]
	ds_read_b128 v[130:133], v54 offset:24576
	s_waitcnt lgkmcnt(7)
	v_pk_fma_f32 v[70:71], v[176:177], v[134:135], v[70:71] op_sel_hi:[0,1,1]
	v_pk_fma_f32 v[86:87], v[180:181], v[134:135], v[86:87] op_sel_hi:[0,1,1]
	v_pk_fma_f32 v[104:105], v[184:185], v[134:135], v[104:105] op_sel_hi:[0,1,1]
	v_pk_fma_f32 v[120:121], v[188:189], v[134:135], v[120:121] op_sel_hi:[0,1,1]
	v_pk_fma_f32 v[72:73], v[176:177], v[136:137], v[72:73] op_sel_hi:[0,1,1]
	v_pk_fma_f32 v[88:89], v[180:181], v[136:137], v[88:89] op_sel_hi:[0,1,1]
	v_pk_fma_f32 v[106:107], v[184:185], v[136:137], v[106:107] op_sel_hi:[0,1,1]
	v_pk_fma_f32 v[122:123], v[188:189], v[136:137], v[122:123] op_sel_hi:[0,1,1]
	ds_read_b128 v[134:137], v55 offset:24576
	s_waitcnt lgkmcnt(7)
	v_pk_fma_f32 v[74:75], v[176:177], v[138:139], v[74:75] op_sel_hi:[0,1,1]
	v_pk_fma_f32 v[90:91], v[180:181], v[138:139], v[90:91] op_sel_hi:[0,1,1]
	v_pk_fma_f32 v[108:109], v[184:185], v[138:139], v[108:109] op_sel_hi:[0,1,1]
	v_pk_fma_f32 v[24:25], v[188:189], v[138:139], v[24:25] op_sel_hi:[0,1,1]
	v_pk_fma_f32 v[76:77], v[176:177], v[140:141], v[76:77] op_sel_hi:[0,1,1]
	v_pk_fma_f32 v[94:95], v[180:181], v[140:141], v[94:95] op_sel_hi:[0,1,1]
	v_pk_fma_f32 v[110:111], v[184:185], v[140:141], v[110:111] op_sel_hi:[0,1,1]
	v_pk_fma_f32 v[26:27], v[188:189], v[140:141], v[26:27] op_sel_hi:[0,1,1]
	ds_read_b128 v[138:141], v56 offset:24576
	s_waitcnt lgkmcnt(7)
	v_pk_fma_f32 v[78:79], v[176:177], v[142:143], v[78:79] op_sel_hi:[0,1,1]
	v_pk_fma_f32 v[96:97], v[180:181], v[142:143], v[96:97] op_sel_hi:[0,1,1]
	v_pk_fma_f32 v[112:113], v[184:185], v[142:143], v[112:113] op_sel_hi:[0,1,1]
	v_pk_fma_f32 v[28:29], v[188:189], v[142:143], v[28:29] op_sel_hi:[0,1,1]
	v_pk_fma_f32 v[80:81], v[176:177], v[144:145], v[80:81] op_sel_hi:[0,1,1]
	v_pk_fma_f32 v[98:99], v[180:181], v[144:145], v[98:99] op_sel_hi:[0,1,1]
	v_pk_fma_f32 v[114:115], v[184:185], v[144:145], v[114:115] op_sel_hi:[0,1,1]
	v_pk_fma_f32 v[30:31], v[188:189], v[144:145], v[30:31] op_sel_hi:[0,1,1]
	ds_read_b128 v[142:145], v57 offset:24576
	s_waitcnt lgkmcnt(7)
	v_pk_fma_f32 v[66:67], v[176:177], v[146:147], v[66:67] op_sel:[1,0,0]
	v_pk_fma_f32 v[82:83], v[180:181], v[146:147], v[82:83] op_sel:[1,0,0]
	v_pk_fma_f32 v[100:101], v[184:185], v[146:147], v[100:101] op_sel:[1,0,0]
	v_pk_fma_f32 v[116:117], v[188:189], v[146:147], v[116:117] op_sel:[1,0,0]
	v_pk_fma_f32 v[68:69], v[176:177], v[148:149], v[68:69] op_sel:[1,0,0]
	v_pk_fma_f32 v[84:85], v[180:181], v[148:149], v[84:85] op_sel:[1,0,0]
	v_pk_fma_f32 v[102:103], v[184:185], v[148:149], v[102:103] op_sel:[1,0,0]
	v_pk_fma_f32 v[118:119], v[188:189], v[148:149], v[118:119] op_sel:[1,0,0]
	ds_read_b128 v[146:149], v54 offset:28672
	s_waitcnt lgkmcnt(7)
	v_pk_fma_f32 v[70:71], v[176:177], v[150:151], v[70:71] op_sel:[1,0,0]
	v_pk_fma_f32 v[86:87], v[180:181], v[150:151], v[86:87] op_sel:[1,0,0]
	v_pk_fma_f32 v[104:105], v[184:185], v[150:151], v[104:105] op_sel:[1,0,0]
	v_pk_fma_f32 v[120:121], v[188:189], v[150:151], v[120:121] op_sel:[1,0,0]
	v_pk_fma_f32 v[72:73], v[176:177], v[152:153], v[72:73] op_sel:[1,0,0]
	v_pk_fma_f32 v[88:89], v[180:181], v[152:153], v[88:89] op_sel:[1,0,0]
	v_pk_fma_f32 v[106:107], v[184:185], v[152:153], v[106:107] op_sel:[1,0,0]
	v_pk_fma_f32 v[122:123], v[188:189], v[152:153], v[122:123] op_sel:[1,0,0]
	ds_read_b128 v[150:153], v55 offset:28672
	s_waitcnt lgkmcnt(7)
	v_pk_fma_f32 v[74:75], v[176:177], v[154:155], v[74:75] op_sel:[1,0,0]
	v_pk_fma_f32 v[90:91], v[180:181], v[154:155], v[90:91] op_sel:[1,0,0]
	v_pk_fma_f32 v[108:109], v[184:185], v[154:155], v[108:109] op_sel:[1,0,0]
	v_pk_fma_f32 v[24:25], v[188:189], v[154:155], v[24:25] op_sel:[1,0,0]
	v_pk_fma_f32 v[76:77], v[176:177], v[156:157], v[76:77] op_sel:[1,0,0]
	v_pk_fma_f32 v[94:95], v[180:181], v[156:157], v[94:95] op_sel:[1,0,0]
	v_pk_fma_f32 v[110:111], v[184:185], v[156:157], v[110:111] op_sel:[1,0,0]
	v_pk_fma_f32 v[26:27], v[188:189], v[156:157], v[26:27] op_sel:[1,0,0]
	ds_read_b128 v[154:157], v56 offset:28672
	s_waitcnt lgkmcnt(7)
	v_pk_fma_f32 v[78:79], v[176:177], v[44:45], v[78:79] op_sel:[1,0,0]
	v_pk_fma_f32 v[96:97], v[180:181], v[44:45], v[96:97] op_sel:[1,0,0]
	v_pk_fma_f32 v[112:113], v[184:185], v[44:45], v[112:113] op_sel:[1,0,0]
	v_pk_fma_f32 v[28:29], v[188:189], v[44:45], v[28:29] op_sel:[1,0,0]
	v_pk_fma_f32 v[80:81], v[176:177], v[46:47], v[80:81] op_sel:[1,0,0]
	v_pk_fma_f32 v[98:99], v[180:181], v[46:47], v[98:99] op_sel:[1,0,0]
	v_pk_fma_f32 v[114:115], v[184:185], v[46:47], v[114:115] op_sel:[1,0,0]
	v_pk_fma_f32 v[30:31], v[188:189], v[46:47], v[30:31] op_sel:[1,0,0]
	ds_read_b128 v[44:47], v57 offset:28672
	s_waitcnt lgkmcnt(7)
	v_pk_fma_f32 v[66:67], v[178:179], v[130:131], v[66:67] op_sel_hi:[0,1,1]
	v_pk_fma_f32 v[82:83], v[182:183], v[130:131], v[82:83] op_sel_hi:[0,1,1]
	v_pk_fma_f32 v[100:101], v[186:187], v[130:131], v[100:101] op_sel_hi:[0,1,1]
	v_pk_fma_f32 v[116:117], v[190:191], v[130:131], v[116:117] op_sel_hi:[0,1,1]
	v_pk_fma_f32 v[68:69], v[178:179], v[132:133], v[68:69] op_sel_hi:[0,1,1]
	v_pk_fma_f32 v[84:85], v[182:183], v[132:133], v[84:85] op_sel_hi:[0,1,1]
	v_pk_fma_f32 v[102:103], v[186:187], v[132:133], v[102:103] op_sel_hi:[0,1,1]
	v_pk_fma_f32 v[118:119], v[190:191], v[132:133], v[118:119] op_sel_hi:[0,1,1]
	ds_read_b128 v[130:133], v54 offset:32768
	s_waitcnt lgkmcnt(7)
	v_pk_fma_f32 v[70:71], v[178:179], v[134:135], v[70:71] op_sel_hi:[0,1,1]
	v_pk_fma_f32 v[86:87], v[182:183], v[134:135], v[86:87] op_sel_hi:[0,1,1]
	v_pk_fma_f32 v[104:105], v[186:187], v[134:135], v[104:105] op_sel_hi:[0,1,1]
	v_pk_fma_f32 v[120:121], v[190:191], v[134:135], v[120:121] op_sel_hi:[0,1,1]
	v_pk_fma_f32 v[72:73], v[178:179], v[136:137], v[72:73] op_sel_hi:[0,1,1]
	v_pk_fma_f32 v[88:89], v[182:183], v[136:137], v[88:89] op_sel_hi:[0,1,1]
	v_pk_fma_f32 v[106:107], v[186:187], v[136:137], v[106:107] op_sel_hi:[0,1,1]
	v_pk_fma_f32 v[122:123], v[190:191], v[136:137], v[122:123] op_sel_hi:[0,1,1]
	ds_read_b128 v[134:137], v55 offset:32768
	s_waitcnt lgkmcnt(7)
	v_pk_fma_f32 v[74:75], v[178:179], v[138:139], v[74:75] op_sel_hi:[0,1,1]
	v_pk_fma_f32 v[90:91], v[182:183], v[138:139], v[90:91] op_sel_hi:[0,1,1]
	v_pk_fma_f32 v[108:109], v[186:187], v[138:139], v[108:109] op_sel_hi:[0,1,1]
	v_pk_fma_f32 v[24:25], v[190:191], v[138:139], v[24:25] op_sel_hi:[0,1,1]
	v_pk_fma_f32 v[76:77], v[178:179], v[140:141], v[76:77] op_sel_hi:[0,1,1]
	v_pk_fma_f32 v[94:95], v[182:183], v[140:141], v[94:95] op_sel_hi:[0,1,1]
	v_pk_fma_f32 v[110:111], v[186:187], v[140:141], v[110:111] op_sel_hi:[0,1,1]
	v_pk_fma_f32 v[26:27], v[190:191], v[140:141], v[26:27] op_sel_hi:[0,1,1]
	ds_read_b128 v[138:141], v56 offset:32768
	s_waitcnt lgkmcnt(7)
	v_pk_fma_f32 v[78:79], v[178:179], v[142:143], v[78:79] op_sel_hi:[0,1,1]
	v_pk_fma_f32 v[96:97], v[182:183], v[142:143], v[96:97] op_sel_hi:[0,1,1]
	v_pk_fma_f32 v[112:113], v[186:187], v[142:143], v[112:113] op_sel_hi:[0,1,1]
	v_pk_fma_f32 v[28:29], v[190:191], v[142:143], v[28:29] op_sel_hi:[0,1,1]
	v_pk_fma_f32 v[80:81], v[178:179], v[144:145], v[80:81] op_sel_hi:[0,1,1]
	v_pk_fma_f32 v[98:99], v[182:183], v[144:145], v[98:99] op_sel_hi:[0,1,1]
	v_pk_fma_f32 v[114:115], v[186:187], v[144:145], v[114:115] op_sel_hi:[0,1,1]
	v_pk_fma_f32 v[30:31], v[190:191], v[144:145], v[30:31] op_sel_hi:[0,1,1]
	ds_read_b128 v[142:145], v57 offset:32768
	s_waitcnt lgkmcnt(7)
	v_pk_fma_f32 v[66:67], v[178:179], v[146:147], v[66:67] op_sel:[1,0,0]
	v_pk_fma_f32 v[82:83], v[182:183], v[146:147], v[82:83] op_sel:[1,0,0]
	v_pk_fma_f32 v[100:101], v[186:187], v[146:147], v[100:101] op_sel:[1,0,0]
	v_pk_fma_f32 v[116:117], v[190:191], v[146:147], v[116:117] op_sel:[1,0,0]
	v_pk_fma_f32 v[68:69], v[178:179], v[148:149], v[68:69] op_sel:[1,0,0]
	v_pk_fma_f32 v[84:85], v[182:183], v[148:149], v[84:85] op_sel:[1,0,0]
	v_pk_fma_f32 v[102:103], v[186:187], v[148:149], v[102:103] op_sel:[1,0,0]
	v_pk_fma_f32 v[118:119], v[190:191], v[148:149], v[118:119] op_sel:[1,0,0]
	ds_read_b128 v[146:149], v54 offset:36864
	s_waitcnt lgkmcnt(7)
	v_pk_fma_f32 v[70:71], v[178:179], v[150:151], v[70:71] op_sel:[1,0,0]
	v_pk_fma_f32 v[86:87], v[182:183], v[150:151], v[86:87] op_sel:[1,0,0]
	v_pk_fma_f32 v[104:105], v[186:187], v[150:151], v[104:105] op_sel:[1,0,0]
	v_pk_fma_f32 v[120:121], v[190:191], v[150:151], v[120:121] op_sel:[1,0,0]
	v_pk_fma_f32 v[72:73], v[178:179], v[152:153], v[72:73] op_sel:[1,0,0]
	v_pk_fma_f32 v[88:89], v[182:183], v[152:153], v[88:89] op_sel:[1,0,0]
	v_pk_fma_f32 v[106:107], v[186:187], v[152:153], v[106:107] op_sel:[1,0,0]
	v_pk_fma_f32 v[122:123], v[190:191], v[152:153], v[122:123] op_sel:[1,0,0]
	ds_read_b128 v[150:153], v55 offset:36864
	s_waitcnt lgkmcnt(7)
	v_pk_fma_f32 v[74:75], v[178:179], v[154:155], v[74:75] op_sel:[1,0,0]
	v_pk_fma_f32 v[90:91], v[182:183], v[154:155], v[90:91] op_sel:[1,0,0]
	v_pk_fma_f32 v[108:109], v[186:187], v[154:155], v[108:109] op_sel:[1,0,0]
	v_pk_fma_f32 v[24:25], v[190:191], v[154:155], v[24:25] op_sel:[1,0,0]
	v_pk_fma_f32 v[76:77], v[178:179], v[156:157], v[76:77] op_sel:[1,0,0]
	v_pk_fma_f32 v[94:95], v[182:183], v[156:157], v[94:95] op_sel:[1,0,0]
	v_pk_fma_f32 v[110:111], v[186:187], v[156:157], v[110:111] op_sel:[1,0,0]
	v_pk_fma_f32 v[26:27], v[190:191], v[156:157], v[26:27] op_sel:[1,0,0]
	ds_read_b128 v[154:157], v56 offset:36864
	s_waitcnt lgkmcnt(7)
	v_pk_fma_f32 v[78:79], v[178:179], v[44:45], v[78:79] op_sel:[1,0,0]
	v_pk_fma_f32 v[96:97], v[182:183], v[44:45], v[96:97] op_sel:[1,0,0]
	v_pk_fma_f32 v[112:113], v[186:187], v[44:45], v[112:113] op_sel:[1,0,0]
	v_pk_fma_f32 v[28:29], v[190:191], v[44:45], v[28:29] op_sel:[1,0,0]
	v_pk_fma_f32 v[80:81], v[178:179], v[46:47], v[80:81] op_sel:[1,0,0]
	v_pk_fma_f32 v[98:99], v[182:183], v[46:47], v[98:99] op_sel:[1,0,0]
	v_pk_fma_f32 v[114:115], v[186:187], v[46:47], v[114:115] op_sel:[1,0,0]
	v_pk_fma_f32 v[30:31], v[190:191], v[46:47], v[30:31] op_sel:[1,0,0]
	ds_read_b128 v[44:47], v57 offset:36864
	global_load_dwordx4 v[176:179], v[38:39], off offset:2048 nt
	global_load_dwordx4 v[180:183], v[8:9], off offset:2048 nt
	global_load_dwordx4 v[184:187], v[10:11], off offset:2048 nt
	global_load_dwordx4 v[188:191], v[12:13], off offset:2048 nt
	s_waitcnt vmcnt(27)
	v_cvt_pk_bf16_f32 v244, v192, v193
	v_cvt_pk_bf16_f32 v245, v194, v195
	global_store_dwordx2 v[14:15], v[244:245], off offset:1024
	v_pk_mul_f32 v[22:23], v[192:193], v[192:193]
	v_pk_fma_f32 v[22:23], v[194:195], v[194:195], v[22:23]
	v_add_f32_e32 v22, v22, v23
	v_add_f32_e32 v240, v240, v22
	s_waitcnt vmcnt(27)
	v_cvt_pk_bf16_f32 v246, v196, v197
	v_cvt_pk_bf16_f32 v247, v198, v199
	global_store_dwordx2 v[16:17], v[246:247], off offset:1024
	v_pk_mul_f32 v[22:23], v[196:197], v[196:197]
	v_pk_fma_f32 v[22:23], v[198:199], v[198:199], v[22:23]
	v_add_f32_e32 v22, v22, v23
	v_add_f32_e32 v241, v241, v22
	s_waitcnt vmcnt(27)
	v_cvt_pk_bf16_f32 v248, v200, v201
	v_cvt_pk_bf16_f32 v249, v202, v203
	global_store_dwordx2 v[18:19], v[248:249], off offset:1024
	v_pk_mul_f32 v[22:23], v[200:201], v[200:201]
	v_pk_fma_f32 v[22:23], v[202:203], v[202:203], v[22:23]
	v_add_f32_e32 v22, v22, v23
	v_add_f32_e32 v242, v242, v22
	s_waitcnt vmcnt(27)
	v_cvt_pk_bf16_f32 v232, v204, v205
	v_cvt_pk_bf16_f32 v233, v206, v207
	global_store_dwordx2 v[20:21], v[232:233], off offset:1024
	v_pk_mul_f32 v[22:23], v[204:205], v[204:205]
	v_pk_fma_f32 v[22:23], v[206:207], v[206:207], v[22:23]
	v_add_f32_e32 v22, v22, v23
	v_add_f32_e32 v243, v243, v22
	s_waitcnt lgkmcnt(7)
	v_pk_fma_f32 v[66:67], v[192:193], v[130:131], v[66:67] op_sel_hi:[0,1,1]
	v_pk_fma_f32 v[82:83], v[196:197], v[130:131], v[82:83] op_sel_hi:[0,1,1]
	v_pk_fma_f32 v[100:101], v[200:201], v[130:131], v[100:101] op_sel_hi:[0,1,1]
	v_pk_fma_f32 v[116:117], v[204:205], v[130:131], v[116:117] op_sel_hi:[0,1,1]
	v_pk_fma_f32 v[68:69], v[192:193], v[132:133], v[68:69] op_sel_hi:[0,1,1]
	v_pk_fma_f32 v[84:85], v[196:197], v[132:133], v[84:85] op_sel_hi:[0,1,1]
	v_pk_fma_f32 v[102:103], v[200:201], v[132:133], v[102:103] op_sel_hi:[0,1,1]
	v_pk_fma_f32 v[118:119], v[204:205], v[132:133], v[118:119] op_sel_hi:[0,1,1]
	ds_read_b128 v[130:133], v54 offset:40960
	s_waitcnt lgkmcnt(7)
	v_pk_fma_f32 v[70:71], v[192:193], v[134:135], v[70:71] op_sel_hi:[0,1,1]
	v_pk_fma_f32 v[86:87], v[196:197], v[134:135], v[86:87] op_sel_hi:[0,1,1]
	v_pk_fma_f32 v[104:105], v[200:201], v[134:135], v[104:105] op_sel_hi:[0,1,1]
	v_pk_fma_f32 v[120:121], v[204:205], v[134:135], v[120:121] op_sel_hi:[0,1,1]
	v_pk_fma_f32 v[72:73], v[192:193], v[136:137], v[72:73] op_sel_hi:[0,1,1]
	v_pk_fma_f32 v[88:89], v[196:197], v[136:137], v[88:89] op_sel_hi:[0,1,1]
	v_pk_fma_f32 v[106:107], v[200:201], v[136:137], v[106:107] op_sel_hi:[0,1,1]
	v_pk_fma_f32 v[122:123], v[204:205], v[136:137], v[122:123] op_sel_hi:[0,1,1]
	ds_read_b128 v[134:137], v55 offset:40960
	s_waitcnt lgkmcnt(7)
	v_pk_fma_f32 v[74:75], v[192:193], v[138:139], v[74:75] op_sel_hi:[0,1,1]
	v_pk_fma_f32 v[90:91], v[196:197], v[138:139], v[90:91] op_sel_hi:[0,1,1]
	v_pk_fma_f32 v[108:109], v[200:201], v[138:139], v[108:109] op_sel_hi:[0,1,1]
	v_pk_fma_f32 v[24:25], v[204:205], v[138:139], v[24:25] op_sel_hi:[0,1,1]
	v_pk_fma_f32 v[76:77], v[192:193], v[140:141], v[76:77] op_sel_hi:[0,1,1]
	v_pk_fma_f32 v[94:95], v[196:197], v[140:141], v[94:95] op_sel_hi:[0,1,1]
	v_pk_fma_f32 v[110:111], v[200:201], v[140:141], v[110:111] op_sel_hi:[0,1,1]
	v_pk_fma_f32 v[26:27], v[204:205], v[140:141], v[26:27] op_sel_hi:[0,1,1]
	ds_read_b128 v[138:141], v56 offset:40960
	s_waitcnt lgkmcnt(7)
	v_pk_fma_f32 v[78:79], v[192:193], v[142:143], v[78:79] op_sel_hi:[0,1,1]
	v_pk_fma_f32 v[96:97], v[196:197], v[142:143], v[96:97] op_sel_hi:[0,1,1]
	v_pk_fma_f32 v[112:113], v[200:201], v[142:143], v[112:113] op_sel_hi:[0,1,1]
	v_pk_fma_f32 v[28:29], v[204:205], v[142:143], v[28:29] op_sel_hi:[0,1,1]
	v_pk_fma_f32 v[80:81], v[192:193], v[144:145], v[80:81] op_sel_hi:[0,1,1]
	v_pk_fma_f32 v[98:99], v[196:197], v[144:145], v[98:99] op_sel_hi:[0,1,1]
	v_pk_fma_f32 v[114:115], v[200:201], v[144:145], v[114:115] op_sel_hi:[0,1,1]
	v_pk_fma_f32 v[30:31], v[204:205], v[144:145], v[30:31] op_sel_hi:[0,1,1]
	ds_read_b128 v[142:145], v57 offset:40960
	s_waitcnt lgkmcnt(7)
	v_pk_fma_f32 v[66:67], v[192:193], v[146:147], v[66:67] op_sel:[1,0,0]
	v_pk_fma_f32 v[82:83], v[196:197], v[146:147], v[82:83] op_sel:[1,0,0]
	v_pk_fma_f32 v[100:101], v[200:201], v[146:147], v[100:101] op_sel:[1,0,0]
	v_pk_fma_f32 v[116:117], v[204:205], v[146:147], v[116:117] op_sel:[1,0,0]
	v_pk_fma_f32 v[68:69], v[192:193], v[148:149], v[68:69] op_sel:[1,0,0]
	v_pk_fma_f32 v[84:85], v[196:197], v[148:149], v[84:85] op_sel:[1,0,0]
	v_pk_fma_f32 v[102:103], v[200:201], v[148:149], v[102:103] op_sel:[1,0,0]
	v_pk_fma_f32 v[118:119], v[204:205], v[148:149], v[118:119] op_sel:[1,0,0]
	ds_read_b128 v[146:149], v54 offset:45056
	s_waitcnt lgkmcnt(7)
	v_pk_fma_f32 v[70:71], v[192:193], v[150:151], v[70:71] op_sel:[1,0,0]
	v_pk_fma_f32 v[86:87], v[196:197], v[150:151], v[86:87] op_sel:[1,0,0]
	v_pk_fma_f32 v[104:105], v[200:201], v[150:151], v[104:105] op_sel:[1,0,0]
	v_pk_fma_f32 v[120:121], v[204:205], v[150:151], v[120:121] op_sel:[1,0,0]
	v_pk_fma_f32 v[72:73], v[192:193], v[152:153], v[72:73] op_sel:[1,0,0]
	v_pk_fma_f32 v[88:89], v[196:197], v[152:153], v[88:89] op_sel:[1,0,0]
	v_pk_fma_f32 v[106:107], v[200:201], v[152:153], v[106:107] op_sel:[1,0,0]
	v_pk_fma_f32 v[122:123], v[204:205], v[152:153], v[122:123] op_sel:[1,0,0]
	ds_read_b128 v[150:153], v55 offset:45056
	s_waitcnt lgkmcnt(7)
	v_pk_fma_f32 v[74:75], v[192:193], v[154:155], v[74:75] op_sel:[1,0,0]
	v_pk_fma_f32 v[90:91], v[196:197], v[154:155], v[90:91] op_sel:[1,0,0]
	v_pk_fma_f32 v[108:109], v[200:201], v[154:155], v[108:109] op_sel:[1,0,0]
	v_pk_fma_f32 v[24:25], v[204:205], v[154:155], v[24:25] op_sel:[1,0,0]
	v_pk_fma_f32 v[76:77], v[192:193], v[156:157], v[76:77] op_sel:[1,0,0]
	v_pk_fma_f32 v[94:95], v[196:197], v[156:157], v[94:95] op_sel:[1,0,0]
	v_pk_fma_f32 v[110:111], v[200:201], v[156:157], v[110:111] op_sel:[1,0,0]
	v_pk_fma_f32 v[26:27], v[204:205], v[156:157], v[26:27] op_sel:[1,0,0]
	ds_read_b128 v[154:157], v56 offset:45056
	s_waitcnt lgkmcnt(7)
	v_pk_fma_f32 v[78:79], v[192:193], v[44:45], v[78:79] op_sel:[1,0,0]
	v_pk_fma_f32 v[96:97], v[196:197], v[44:45], v[96:97] op_sel:[1,0,0]
	v_pk_fma_f32 v[112:113], v[200:201], v[44:45], v[112:113] op_sel:[1,0,0]
	v_pk_fma_f32 v[28:29], v[204:205], v[44:45], v[28:29] op_sel:[1,0,0]
	v_pk_fma_f32 v[80:81], v[192:193], v[46:47], v[80:81] op_sel:[1,0,0]
	v_pk_fma_f32 v[98:99], v[196:197], v[46:47], v[98:99] op_sel:[1,0,0]
	v_pk_fma_f32 v[114:115], v[200:201], v[46:47], v[114:115] op_sel:[1,0,0]
	v_pk_fma_f32 v[30:31], v[204:205], v[46:47], v[30:31] op_sel:[1,0,0]
	ds_read_b128 v[44:47], v57 offset:45056
	s_waitcnt lgkmcnt(7)
	v_pk_fma_f32 v[66:67], v[194:195], v[130:131], v[66:67] op_sel_hi:[0,1,1]
	v_pk_fma_f32 v[82:83], v[198:199], v[130:131], v[82:83] op_sel_hi:[0,1,1]
	v_pk_fma_f32 v[100:101], v[202:203], v[130:131], v[100:101] op_sel_hi:[0,1,1]
	v_pk_fma_f32 v[116:117], v[206:207], v[130:131], v[116:117] op_sel_hi:[0,1,1]
	v_pk_fma_f32 v[68:69], v[194:195], v[132:133], v[68:69] op_sel_hi:[0,1,1]
	v_pk_fma_f32 v[84:85], v[198:199], v[132:133], v[84:85] op_sel_hi:[0,1,1]
	v_pk_fma_f32 v[102:103], v[202:203], v[132:133], v[102:103] op_sel_hi:[0,1,1]
	v_pk_fma_f32 v[118:119], v[206:207], v[132:133], v[118:119] op_sel_hi:[0,1,1]
	ds_read_b128 v[130:133], v54 offset:49152
	s_waitcnt lgkmcnt(7)
	v_pk_fma_f32 v[70:71], v[194:195], v[134:135], v[70:71] op_sel_hi:[0,1,1]
	v_pk_fma_f32 v[86:87], v[198:199], v[134:135], v[86:87] op_sel_hi:[0,1,1]
	v_pk_fma_f32 v[104:105], v[202:203], v[134:135], v[104:105] op_sel_hi:[0,1,1]
	v_pk_fma_f32 v[120:121], v[206:207], v[134:135], v[120:121] op_sel_hi:[0,1,1]
	v_pk_fma_f32 v[72:73], v[194:195], v[136:137], v[72:73] op_sel_hi:[0,1,1]
	v_pk_fma_f32 v[88:89], v[198:199], v[136:137], v[88:89] op_sel_hi:[0,1,1]
	v_pk_fma_f32 v[106:107], v[202:203], v[136:137], v[106:107] op_sel_hi:[0,1,1]
	v_pk_fma_f32 v[122:123], v[206:207], v[136:137], v[122:123] op_sel_hi:[0,1,1]
	ds_read_b128 v[134:137], v55 offset:49152
	s_waitcnt lgkmcnt(7)
	v_pk_fma_f32 v[74:75], v[194:195], v[138:139], v[74:75] op_sel_hi:[0,1,1]
	v_pk_fma_f32 v[90:91], v[198:199], v[138:139], v[90:91] op_sel_hi:[0,1,1]
	v_pk_fma_f32 v[108:109], v[202:203], v[138:139], v[108:109] op_sel_hi:[0,1,1]
	v_pk_fma_f32 v[24:25], v[206:207], v[138:139], v[24:25] op_sel_hi:[0,1,1]
	v_pk_fma_f32 v[76:77], v[194:195], v[140:141], v[76:77] op_sel_hi:[0,1,1]
	v_pk_fma_f32 v[94:95], v[198:199], v[140:141], v[94:95] op_sel_hi:[0,1,1]
	v_pk_fma_f32 v[110:111], v[202:203], v[140:141], v[110:111] op_sel_hi:[0,1,1]
	v_pk_fma_f32 v[26:27], v[206:207], v[140:141], v[26:27] op_sel_hi:[0,1,1]
	ds_read_b128 v[138:141], v56 offset:49152
	s_waitcnt lgkmcnt(7)
	v_pk_fma_f32 v[78:79], v[194:195], v[142:143], v[78:79] op_sel_hi:[0,1,1]
	v_pk_fma_f32 v[96:97], v[198:199], v[142:143], v[96:97] op_sel_hi:[0,1,1]
	v_pk_fma_f32 v[112:113], v[202:203], v[142:143], v[112:113] op_sel_hi:[0,1,1]
	v_pk_fma_f32 v[28:29], v[206:207], v[142:143], v[28:29] op_sel_hi:[0,1,1]
	v_pk_fma_f32 v[80:81], v[194:195], v[144:145], v[80:81] op_sel_hi:[0,1,1]
	v_pk_fma_f32 v[98:99], v[198:199], v[144:145], v[98:99] op_sel_hi:[0,1,1]
	v_pk_fma_f32 v[114:115], v[202:203], v[144:145], v[114:115] op_sel_hi:[0,1,1]
	v_pk_fma_f32 v[30:31], v[206:207], v[144:145], v[30:31] op_sel_hi:[0,1,1]
	ds_read_b128 v[142:145], v57 offset:49152
	s_waitcnt lgkmcnt(7)
	v_pk_fma_f32 v[66:67], v[194:195], v[146:147], v[66:67] op_sel:[1,0,0]
	v_pk_fma_f32 v[82:83], v[198:199], v[146:147], v[82:83] op_sel:[1,0,0]
	v_pk_fma_f32 v[100:101], v[202:203], v[146:147], v[100:101] op_sel:[1,0,0]
	v_pk_fma_f32 v[116:117], v[206:207], v[146:147], v[116:117] op_sel:[1,0,0]
	v_pk_fma_f32 v[68:69], v[194:195], v[148:149], v[68:69] op_sel:[1,0,0]
	v_pk_fma_f32 v[84:85], v[198:199], v[148:149], v[84:85] op_sel:[1,0,0]
	v_pk_fma_f32 v[102:103], v[202:203], v[148:149], v[102:103] op_sel:[1,0,0]
	v_pk_fma_f32 v[118:119], v[206:207], v[148:149], v[118:119] op_sel:[1,0,0]
	ds_read_b128 v[146:149], v54 offset:53248
	s_waitcnt lgkmcnt(7)
	v_pk_fma_f32 v[70:71], v[194:195], v[150:151], v[70:71] op_sel:[1,0,0]
	v_pk_fma_f32 v[86:87], v[198:199], v[150:151], v[86:87] op_sel:[1,0,0]
	v_pk_fma_f32 v[104:105], v[202:203], v[150:151], v[104:105] op_sel:[1,0,0]
	v_pk_fma_f32 v[120:121], v[206:207], v[150:151], v[120:121] op_sel:[1,0,0]
	v_pk_fma_f32 v[72:73], v[194:195], v[152:153], v[72:73] op_sel:[1,0,0]
	v_pk_fma_f32 v[88:89], v[198:199], v[152:153], v[88:89] op_sel:[1,0,0]
	v_pk_fma_f32 v[106:107], v[202:203], v[152:153], v[106:107] op_sel:[1,0,0]
	v_pk_fma_f32 v[122:123], v[206:207], v[152:153], v[122:123] op_sel:[1,0,0]
	ds_read_b128 v[150:153], v55 offset:53248
	s_waitcnt lgkmcnt(7)
	v_pk_fma_f32 v[74:75], v[194:195], v[154:155], v[74:75] op_sel:[1,0,0]
	v_pk_fma_f32 v[90:91], v[198:199], v[154:155], v[90:91] op_sel:[1,0,0]
	v_pk_fma_f32 v[108:109], v[202:203], v[154:155], v[108:109] op_sel:[1,0,0]
	v_pk_fma_f32 v[24:25], v[206:207], v[154:155], v[24:25] op_sel:[1,0,0]
	v_pk_fma_f32 v[76:77], v[194:195], v[156:157], v[76:77] op_sel:[1,0,0]
	v_pk_fma_f32 v[94:95], v[198:199], v[156:157], v[94:95] op_sel:[1,0,0]
	v_pk_fma_f32 v[110:111], v[202:203], v[156:157], v[110:111] op_sel:[1,0,0]
	v_pk_fma_f32 v[26:27], v[206:207], v[156:157], v[26:27] op_sel:[1,0,0]
	ds_read_b128 v[154:157], v56 offset:53248
	s_waitcnt lgkmcnt(7)
	v_pk_fma_f32 v[78:79], v[194:195], v[44:45], v[78:79] op_sel:[1,0,0]
	v_pk_fma_f32 v[96:97], v[198:199], v[44:45], v[96:97] op_sel:[1,0,0]
	v_pk_fma_f32 v[112:113], v[202:203], v[44:45], v[112:113] op_sel:[1,0,0]
	v_pk_fma_f32 v[28:29], v[206:207], v[44:45], v[28:29] op_sel:[1,0,0]
	v_pk_fma_f32 v[80:81], v[194:195], v[46:47], v[80:81] op_sel:[1,0,0]
	v_pk_fma_f32 v[98:99], v[198:199], v[46:47], v[98:99] op_sel:[1,0,0]
	v_pk_fma_f32 v[114:115], v[202:203], v[46:47], v[114:115] op_sel:[1,0,0]
	v_pk_fma_f32 v[30:31], v[206:207], v[46:47], v[30:31] op_sel:[1,0,0]
	ds_read_b128 v[44:47], v57 offset:53248
	global_load_dwordx4 v[192:195], v[38:39], off offset:3072 nt
	global_load_dwordx4 v[196:199], v[8:9], off offset:3072 nt
	global_load_dwordx4 v[200:203], v[10:11], off offset:3072 nt
	global_load_dwordx4 v[204:207], v[12:13], off offset:3072 nt
	s_waitcnt vmcnt(31)
	v_cvt_pk_bf16_f32 v244, v208, v209
	v_cvt_pk_bf16_f32 v245, v210, v211
	global_store_dwordx2 v[14:15], v[244:245], off offset:1536
	v_pk_mul_f32 v[22:23], v[208:209], v[208:209]
	v_pk_fma_f32 v[22:23], v[210:211], v[210:211], v[22:23]
	v_add_f32_e32 v22, v22, v23
	v_add_f32_e32 v240, v240, v22
	s_waitcnt vmcnt(31)
	v_cvt_pk_bf16_f32 v246, v212, v213
	v_cvt_pk_bf16_f32 v247, v214, v215
	global_store_dwordx2 v[16:17], v[246:247], off offset:1536
	v_pk_mul_f32 v[22:23], v[212:213], v[212:213]
	v_pk_fma_f32 v[22:23], v[214:215], v[214:215], v[22:23]
	v_add_f32_e32 v22, v22, v23
	v_add_f32_e32 v241, v241, v22
	s_waitcnt vmcnt(31)
	v_cvt_pk_bf16_f32 v248, v216, v217
	v_cvt_pk_bf16_f32 v249, v218, v219
	global_store_dwordx2 v[18:19], v[248:249], off offset:1536
	v_pk_mul_f32 v[22:23], v[216:217], v[216:217]
	v_pk_fma_f32 v[22:23], v[218:219], v[218:219], v[22:23]
	v_add_f32_e32 v22, v22, v23
	v_add_f32_e32 v242, v242, v22
	s_waitcnt vmcnt(31)
	v_cvt_pk_bf16_f32 v232, v220, v221
	v_cvt_pk_bf16_f32 v233, v222, v223
	global_store_dwordx2 v[20:21], v[232:233], off offset:1536
	v_pk_mul_f32 v[22:23], v[220:221], v[220:221]
	v_pk_fma_f32 v[22:23], v[222:223], v[222:223], v[22:23]
	v_add_f32_e32 v22, v22, v23
	v_add_f32_e32 v243, v243, v22
	s_waitcnt lgkmcnt(7)
	v_pk_fma_f32 v[66:67], v[208:209], v[130:131], v[66:67] op_sel_hi:[0,1,1]
	v_pk_fma_f32 v[82:83], v[212:213], v[130:131], v[82:83] op_sel_hi:[0,1,1]
	v_pk_fma_f32 v[100:101], v[216:217], v[130:131], v[100:101] op_sel_hi:[0,1,1]
	v_pk_fma_f32 v[116:117], v[220:221], v[130:131], v[116:117] op_sel_hi:[0,1,1]
	v_pk_fma_f32 v[68:69], v[208:209], v[132:133], v[68:69] op_sel_hi:[0,1,1]
	v_pk_fma_f32 v[84:85], v[212:213], v[132:133], v[84:85] op_sel_hi:[0,1,1]
	v_pk_fma_f32 v[102:103], v[216:217], v[132:133], v[102:103] op_sel_hi:[0,1,1]
	v_pk_fma_f32 v[118:119], v[220:221], v[132:133], v[118:119] op_sel_hi:[0,1,1]
	ds_read_b128 v[130:133], v54 offset:57344
	s_waitcnt lgkmcnt(7)
	v_pk_fma_f32 v[70:71], v[208:209], v[134:135], v[70:71] op_sel_hi:[0,1,1]
	v_pk_fma_f32 v[86:87], v[212:213], v[134:135], v[86:87] op_sel_hi:[0,1,1]
	v_pk_fma_f32 v[104:105], v[216:217], v[134:135], v[104:105] op_sel_hi:[0,1,1]
	v_pk_fma_f32 v[120:121], v[220:221], v[134:135], v[120:121] op_sel_hi:[0,1,1]
	v_pk_fma_f32 v[72:73], v[208:209], v[136:137], v[72:73] op_sel_hi:[0,1,1]
	v_pk_fma_f32 v[88:89], v[212:213], v[136:137], v[88:89] op_sel_hi:[0,1,1]
	v_pk_fma_f32 v[106:107], v[216:217], v[136:137], v[106:107] op_sel_hi:[0,1,1]
	v_pk_fma_f32 v[122:123], v[220:221], v[136:137], v[122:123] op_sel_hi:[0,1,1]
	ds_read_b128 v[134:137], v55 offset:57344
	s_waitcnt lgkmcnt(7)
	v_pk_fma_f32 v[74:75], v[208:209], v[138:139], v[74:75] op_sel_hi:[0,1,1]
	v_pk_fma_f32 v[90:91], v[212:213], v[138:139], v[90:91] op_sel_hi:[0,1,1]
	v_pk_fma_f32 v[108:109], v[216:217], v[138:139], v[108:109] op_sel_hi:[0,1,1]
	v_pk_fma_f32 v[24:25], v[220:221], v[138:139], v[24:25] op_sel_hi:[0,1,1]
	v_pk_fma_f32 v[76:77], v[208:209], v[140:141], v[76:77] op_sel_hi:[0,1,1]
	v_pk_fma_f32 v[94:95], v[212:213], v[140:141], v[94:95] op_sel_hi:[0,1,1]
	v_pk_fma_f32 v[110:111], v[216:217], v[140:141], v[110:111] op_sel_hi:[0,1,1]
	v_pk_fma_f32 v[26:27], v[220:221], v[140:141], v[26:27] op_sel_hi:[0,1,1]
	ds_read_b128 v[138:141], v56 offset:57344
	s_waitcnt lgkmcnt(7)
	v_pk_fma_f32 v[78:79], v[208:209], v[142:143], v[78:79] op_sel_hi:[0,1,1]
	v_pk_fma_f32 v[96:97], v[212:213], v[142:143], v[96:97] op_sel_hi:[0,1,1]
	v_pk_fma_f32 v[112:113], v[216:217], v[142:143], v[112:113] op_sel_hi:[0,1,1]
	v_pk_fma_f32 v[28:29], v[220:221], v[142:143], v[28:29] op_sel_hi:[0,1,1]
	v_pk_fma_f32 v[80:81], v[208:209], v[144:145], v[80:81] op_sel_hi:[0,1,1]
	v_pk_fma_f32 v[98:99], v[212:213], v[144:145], v[98:99] op_sel_hi:[0,1,1]
	v_pk_fma_f32 v[114:115], v[216:217], v[144:145], v[114:115] op_sel_hi:[0,1,1]
	v_pk_fma_f32 v[30:31], v[220:221], v[144:145], v[30:31] op_sel_hi:[0,1,1]
	ds_read_b128 v[142:145], v57 offset:57344
	s_waitcnt lgkmcnt(7)
	v_pk_fma_f32 v[66:67], v[208:209], v[146:147], v[66:67] op_sel:[1,0,0]
	v_pk_fma_f32 v[82:83], v[212:213], v[146:147], v[82:83] op_sel:[1,0,0]
	v_pk_fma_f32 v[100:101], v[216:217], v[146:147], v[100:101] op_sel:[1,0,0]
	v_pk_fma_f32 v[116:117], v[220:221], v[146:147], v[116:117] op_sel:[1,0,0]
	v_pk_fma_f32 v[68:69], v[208:209], v[148:149], v[68:69] op_sel:[1,0,0]
	v_pk_fma_f32 v[84:85], v[212:213], v[148:149], v[84:85] op_sel:[1,0,0]
	v_pk_fma_f32 v[102:103], v[216:217], v[148:149], v[102:103] op_sel:[1,0,0]
	v_pk_fma_f32 v[118:119], v[220:221], v[148:149], v[118:119] op_sel:[1,0,0]
	ds_read_b128 v[146:149], v54 offset:61440
	s_waitcnt lgkmcnt(7)
	v_pk_fma_f32 v[70:71], v[208:209], v[150:151], v[70:71] op_sel:[1,0,0]
	v_pk_fma_f32 v[86:87], v[212:213], v[150:151], v[86:87] op_sel:[1,0,0]
	v_pk_fma_f32 v[104:105], v[216:217], v[150:151], v[104:105] op_sel:[1,0,0]
	v_pk_fma_f32 v[120:121], v[220:221], v[150:151], v[120:121] op_sel:[1,0,0]
	v_pk_fma_f32 v[72:73], v[208:209], v[152:153], v[72:73] op_sel:[1,0,0]
	v_pk_fma_f32 v[88:89], v[212:213], v[152:153], v[88:89] op_sel:[1,0,0]
	v_pk_fma_f32 v[106:107], v[216:217], v[152:153], v[106:107] op_sel:[1,0,0]
	v_pk_fma_f32 v[122:123], v[220:221], v[152:153], v[122:123] op_sel:[1,0,0]
	ds_read_b128 v[150:153], v55 offset:61440
	s_waitcnt lgkmcnt(7)
	v_pk_fma_f32 v[74:75], v[208:209], v[154:155], v[74:75] op_sel:[1,0,0]
	v_pk_fma_f32 v[90:91], v[212:213], v[154:155], v[90:91] op_sel:[1,0,0]
	v_pk_fma_f32 v[108:109], v[216:217], v[154:155], v[108:109] op_sel:[1,0,0]
	v_pk_fma_f32 v[24:25], v[220:221], v[154:155], v[24:25] op_sel:[1,0,0]
	v_pk_fma_f32 v[76:77], v[208:209], v[156:157], v[76:77] op_sel:[1,0,0]
	v_pk_fma_f32 v[94:95], v[212:213], v[156:157], v[94:95] op_sel:[1,0,0]
	v_pk_fma_f32 v[110:111], v[216:217], v[156:157], v[110:111] op_sel:[1,0,0]
	v_pk_fma_f32 v[26:27], v[220:221], v[156:157], v[26:27] op_sel:[1,0,0]
	ds_read_b128 v[154:157], v56 offset:61440
	s_waitcnt lgkmcnt(7)
	v_pk_fma_f32 v[78:79], v[208:209], v[44:45], v[78:79] op_sel:[1,0,0]
	v_pk_fma_f32 v[96:97], v[212:213], v[44:45], v[96:97] op_sel:[1,0,0]
	v_pk_fma_f32 v[112:113], v[216:217], v[44:45], v[112:113] op_sel:[1,0,0]
	v_pk_fma_f32 v[28:29], v[220:221], v[44:45], v[28:29] op_sel:[1,0,0]
	v_pk_fma_f32 v[80:81], v[208:209], v[46:47], v[80:81] op_sel:[1,0,0]
	v_pk_fma_f32 v[98:99], v[212:213], v[46:47], v[98:99] op_sel:[1,0,0]
	v_pk_fma_f32 v[114:115], v[216:217], v[46:47], v[114:115] op_sel:[1,0,0]
	v_pk_fma_f32 v[30:31], v[220:221], v[46:47], v[30:31] op_sel:[1,0,0]
	ds_read_b128 v[44:47], v57 offset:61440
	s_waitcnt lgkmcnt(7)
	v_pk_fma_f32 v[66:67], v[210:211], v[130:131], v[66:67] op_sel_hi:[0,1,1]
	v_pk_fma_f32 v[82:83], v[214:215], v[130:131], v[82:83] op_sel_hi:[0,1,1]
	v_pk_fma_f32 v[100:101], v[218:219], v[130:131], v[100:101] op_sel_hi:[0,1,1]
	v_pk_fma_f32 v[116:117], v[222:223], v[130:131], v[116:117] op_sel_hi:[0,1,1]
	v_pk_fma_f32 v[68:69], v[210:211], v[132:133], v[68:69] op_sel_hi:[0,1,1]
	v_pk_fma_f32 v[84:85], v[214:215], v[132:133], v[84:85] op_sel_hi:[0,1,1]
	v_pk_fma_f32 v[102:103], v[218:219], v[132:133], v[102:103] op_sel_hi:[0,1,1]
	v_pk_fma_f32 v[118:119], v[222:223], v[132:133], v[118:119] op_sel_hi:[0,1,1]
	ds_read_b128 v[130:133], v58
	s_waitcnt lgkmcnt(7)
	v_pk_fma_f32 v[70:71], v[210:211], v[134:135], v[70:71] op_sel_hi:[0,1,1]
	v_pk_fma_f32 v[86:87], v[214:215], v[134:135], v[86:87] op_sel_hi:[0,1,1]
	v_pk_fma_f32 v[104:105], v[218:219], v[134:135], v[104:105] op_sel_hi:[0,1,1]
	v_pk_fma_f32 v[120:121], v[222:223], v[134:135], v[120:121] op_sel_hi:[0,1,1]
	v_pk_fma_f32 v[72:73], v[210:211], v[136:137], v[72:73] op_sel_hi:[0,1,1]
	v_pk_fma_f32 v[88:89], v[214:215], v[136:137], v[88:89] op_sel_hi:[0,1,1]
	v_pk_fma_f32 v[106:107], v[218:219], v[136:137], v[106:107] op_sel_hi:[0,1,1]
	v_pk_fma_f32 v[122:123], v[222:223], v[136:137], v[122:123] op_sel_hi:[0,1,1]
	ds_read_b128 v[134:137], v59
	s_waitcnt lgkmcnt(7)
	v_pk_fma_f32 v[74:75], v[210:211], v[138:139], v[74:75] op_sel_hi:[0,1,1]
	v_pk_fma_f32 v[90:91], v[214:215], v[138:139], v[90:91] op_sel_hi:[0,1,1]
	v_pk_fma_f32 v[108:109], v[218:219], v[138:139], v[108:109] op_sel_hi:[0,1,1]
	v_pk_fma_f32 v[24:25], v[222:223], v[138:139], v[24:25] op_sel_hi:[0,1,1]
	v_pk_fma_f32 v[76:77], v[210:211], v[140:141], v[76:77] op_sel_hi:[0,1,1]
	v_pk_fma_f32 v[94:95], v[214:215], v[140:141], v[94:95] op_sel_hi:[0,1,1]
	v_pk_fma_f32 v[110:111], v[218:219], v[140:141], v[110:111] op_sel_hi:[0,1,1]
	v_pk_fma_f32 v[26:27], v[222:223], v[140:141], v[26:27] op_sel_hi:[0,1,1]
	ds_read_b128 v[138:141], v60
	s_waitcnt lgkmcnt(7)
	v_pk_fma_f32 v[78:79], v[210:211], v[142:143], v[78:79] op_sel_hi:[0,1,1]
	v_pk_fma_f32 v[96:97], v[214:215], v[142:143], v[96:97] op_sel_hi:[0,1,1]
	v_pk_fma_f32 v[112:113], v[218:219], v[142:143], v[112:113] op_sel_hi:[0,1,1]
	v_pk_fma_f32 v[28:29], v[222:223], v[142:143], v[28:29] op_sel_hi:[0,1,1]
	v_pk_fma_f32 v[80:81], v[210:211], v[144:145], v[80:81] op_sel_hi:[0,1,1]
	v_pk_fma_f32 v[98:99], v[214:215], v[144:145], v[98:99] op_sel_hi:[0,1,1]
	v_pk_fma_f32 v[114:115], v[218:219], v[144:145], v[114:115] op_sel_hi:[0,1,1]
	v_pk_fma_f32 v[30:31], v[222:223], v[144:145], v[30:31] op_sel_hi:[0,1,1]
	ds_read_b128 v[142:145], v61
	s_waitcnt lgkmcnt(7)
	v_pk_fma_f32 v[66:67], v[210:211], v[146:147], v[66:67] op_sel:[1,0,0]
	v_pk_fma_f32 v[82:83], v[214:215], v[146:147], v[82:83] op_sel:[1,0,0]
	v_pk_fma_f32 v[100:101], v[218:219], v[146:147], v[100:101] op_sel:[1,0,0]
	v_pk_fma_f32 v[116:117], v[222:223], v[146:147], v[116:117] op_sel:[1,0,0]
	v_pk_fma_f32 v[68:69], v[210:211], v[148:149], v[68:69] op_sel:[1,0,0]
	v_pk_fma_f32 v[84:85], v[214:215], v[148:149], v[84:85] op_sel:[1,0,0]
	v_pk_fma_f32 v[102:103], v[218:219], v[148:149], v[102:103] op_sel:[1,0,0]
	v_pk_fma_f32 v[118:119], v[222:223], v[148:149], v[118:119] op_sel:[1,0,0]
	ds_read_b128 v[146:149], v58 offset:4096
	s_waitcnt lgkmcnt(7)
	v_pk_fma_f32 v[70:71], v[210:211], v[150:151], v[70:71] op_sel:[1,0,0]
	v_pk_fma_f32 v[86:87], v[214:215], v[150:151], v[86:87] op_sel:[1,0,0]
	v_pk_fma_f32 v[104:105], v[218:219], v[150:151], v[104:105] op_sel:[1,0,0]
	v_pk_fma_f32 v[120:121], v[222:223], v[150:151], v[120:121] op_sel:[1,0,0]
	v_pk_fma_f32 v[72:73], v[210:211], v[152:153], v[72:73] op_sel:[1,0,0]
	v_pk_fma_f32 v[88:89], v[214:215], v[152:153], v[88:89] op_sel:[1,0,0]
	v_pk_fma_f32 v[106:107], v[218:219], v[152:153], v[106:107] op_sel:[1,0,0]
	v_pk_fma_f32 v[122:123], v[222:223], v[152:153], v[122:123] op_sel:[1,0,0]
	ds_read_b128 v[150:153], v59 offset:4096
	s_waitcnt lgkmcnt(7)
	v_pk_fma_f32 v[74:75], v[210:211], v[154:155], v[74:75] op_sel:[1,0,0]
	v_pk_fma_f32 v[90:91], v[214:215], v[154:155], v[90:91] op_sel:[1,0,0]
	v_pk_fma_f32 v[108:109], v[218:219], v[154:155], v[108:109] op_sel:[1,0,0]
	v_pk_fma_f32 v[24:25], v[222:223], v[154:155], v[24:25] op_sel:[1,0,0]
	v_pk_fma_f32 v[76:77], v[210:211], v[156:157], v[76:77] op_sel:[1,0,0]
	v_pk_fma_f32 v[94:95], v[214:215], v[156:157], v[94:95] op_sel:[1,0,0]
	v_pk_fma_f32 v[110:111], v[218:219], v[156:157], v[110:111] op_sel:[1,0,0]
	v_pk_fma_f32 v[26:27], v[222:223], v[156:157], v[26:27] op_sel:[1,0,0]
	ds_read_b128 v[154:157], v60 offset:4096
	s_waitcnt lgkmcnt(7)
	v_pk_fma_f32 v[78:79], v[210:211], v[44:45], v[78:79] op_sel:[1,0,0]
	v_pk_fma_f32 v[96:97], v[214:215], v[44:45], v[96:97] op_sel:[1,0,0]
	v_pk_fma_f32 v[112:113], v[218:219], v[44:45], v[112:113] op_sel:[1,0,0]
	v_pk_fma_f32 v[28:29], v[222:223], v[44:45], v[28:29] op_sel:[1,0,0]
	v_pk_fma_f32 v[80:81], v[210:211], v[46:47], v[80:81] op_sel:[1,0,0]
	v_pk_fma_f32 v[98:99], v[214:215], v[46:47], v[98:99] op_sel:[1,0,0]
	v_pk_fma_f32 v[114:115], v[218:219], v[46:47], v[114:115] op_sel:[1,0,0]
	v_pk_fma_f32 v[30:31], v[222:223], v[46:47], v[30:31] op_sel:[1,0,0]
	ds_read_b128 v[44:47], v61 offset:4096
	s_waitcnt vmcnt(31)
	v_cvt_pk_bf16_f32 v244, v224, v225
	v_cvt_pk_bf16_f32 v245, v226, v227
	global_store_dwordx2 v[14:15], v[244:245], off offset:2048
	v_pk_mul_f32 v[22:23], v[224:225], v[224:225]
	v_pk_fma_f32 v[22:23], v[226:227], v[226:227], v[22:23]
	v_add_f32_e32 v22, v22, v23
	v_add_f32_e32 v240, v240, v22
	s_waitcnt vmcnt(31)
	v_cvt_pk_bf16_f32 v246, v228, v229
	v_cvt_pk_bf16_f32 v247, v230, v231
	global_store_dwordx2 v[16:17], v[246:247], off offset:2048
	v_pk_mul_f32 v[22:23], v[228:229], v[228:229]
	v_pk_fma_f32 v[22:23], v[230:231], v[230:231], v[22:23]
	v_add_f32_e32 v22, v22, v23
	v_add_f32_e32 v241, v241, v22
	s_waitcnt vmcnt(31)
	v_cvt_pk_bf16_f32 v248, v0, v1
	v_cvt_pk_bf16_f32 v249, v2, v3
	global_store_dwordx2 v[18:19], v[248:249], off offset:2048
	v_pk_mul_f32 v[22:23], v[0:1], v[0:1]
	v_pk_fma_f32 v[22:23], v[2:3], v[2:3], v[22:23]
	v_add_f32_e32 v22, v22, v23
	v_add_f32_e32 v242, v242, v22
	s_waitcnt vmcnt(31)
	v_cvt_pk_bf16_f32 v232, v4, v5
	v_cvt_pk_bf16_f32 v233, v6, v7
	global_store_dwordx2 v[20:21], v[232:233], off offset:2048
	v_pk_mul_f32 v[22:23], v[4:5], v[4:5]
	v_pk_fma_f32 v[22:23], v[6:7], v[6:7], v[22:23]
	v_add_f32_e32 v22, v22, v23
	v_add_f32_e32 v243, v243, v22
	s_waitcnt lgkmcnt(7)
	v_pk_fma_f32 v[66:67], v[224:225], v[130:131], v[66:67] op_sel_hi:[0,1,1]
	v_pk_fma_f32 v[82:83], v[228:229], v[130:131], v[82:83] op_sel_hi:[0,1,1]
	v_pk_fma_f32 v[100:101], v[0:1], v[130:131], v[100:101] op_sel_hi:[0,1,1]
	v_pk_fma_f32 v[116:117], v[4:5], v[130:131], v[116:117] op_sel_hi:[0,1,1]
	v_pk_fma_f32 v[68:69], v[224:225], v[132:133], v[68:69] op_sel_hi:[0,1,1]
	v_pk_fma_f32 v[84:85], v[228:229], v[132:133], v[84:85] op_sel_hi:[0,1,1]
	v_pk_fma_f32 v[102:103], v[0:1], v[132:133], v[102:103] op_sel_hi:[0,1,1]
	v_pk_fma_f32 v[118:119], v[4:5], v[132:133], v[118:119] op_sel_hi:[0,1,1]
	ds_read_b128 v[130:133], v58 offset:8192
	s_waitcnt lgkmcnt(7)
	v_pk_fma_f32 v[70:71], v[224:225], v[134:135], v[70:71] op_sel_hi:[0,1,1]
	v_pk_fma_f32 v[86:87], v[228:229], v[134:135], v[86:87] op_sel_hi:[0,1,1]
	v_pk_fma_f32 v[104:105], v[0:1], v[134:135], v[104:105] op_sel_hi:[0,1,1]
	v_pk_fma_f32 v[120:121], v[4:5], v[134:135], v[120:121] op_sel_hi:[0,1,1]
	v_pk_fma_f32 v[72:73], v[224:225], v[136:137], v[72:73] op_sel_hi:[0,1,1]
	v_pk_fma_f32 v[88:89], v[228:229], v[136:137], v[88:89] op_sel_hi:[0,1,1]
	v_pk_fma_f32 v[106:107], v[0:1], v[136:137], v[106:107] op_sel_hi:[0,1,1]
	v_pk_fma_f32 v[122:123], v[4:5], v[136:137], v[122:123] op_sel_hi:[0,1,1]
	ds_read_b128 v[134:137], v59 offset:8192
	s_waitcnt lgkmcnt(7)
	v_pk_fma_f32 v[74:75], v[224:225], v[138:139], v[74:75] op_sel_hi:[0,1,1]
	v_pk_fma_f32 v[90:91], v[228:229], v[138:139], v[90:91] op_sel_hi:[0,1,1]
	v_pk_fma_f32 v[108:109], v[0:1], v[138:139], v[108:109] op_sel_hi:[0,1,1]
	v_pk_fma_f32 v[24:25], v[4:5], v[138:139], v[24:25] op_sel_hi:[0,1,1]
	v_pk_fma_f32 v[76:77], v[224:225], v[140:141], v[76:77] op_sel_hi:[0,1,1]
	v_pk_fma_f32 v[94:95], v[228:229], v[140:141], v[94:95] op_sel_hi:[0,1,1]
	v_pk_fma_f32 v[110:111], v[0:1], v[140:141], v[110:111] op_sel_hi:[0,1,1]
	v_pk_fma_f32 v[26:27], v[4:5], v[140:141], v[26:27] op_sel_hi:[0,1,1]
	ds_read_b128 v[138:141], v60 offset:8192
	s_waitcnt lgkmcnt(7)
	v_pk_fma_f32 v[78:79], v[224:225], v[142:143], v[78:79] op_sel_hi:[0,1,1]
	v_pk_fma_f32 v[96:97], v[228:229], v[142:143], v[96:97] op_sel_hi:[0,1,1]
	v_pk_fma_f32 v[112:113], v[0:1], v[142:143], v[112:113] op_sel_hi:[0,1,1]
	v_pk_fma_f32 v[28:29], v[4:5], v[142:143], v[28:29] op_sel_hi:[0,1,1]
	v_pk_fma_f32 v[80:81], v[224:225], v[144:145], v[80:81] op_sel_hi:[0,1,1]
	v_pk_fma_f32 v[98:99], v[228:229], v[144:145], v[98:99] op_sel_hi:[0,1,1]
	v_pk_fma_f32 v[114:115], v[0:1], v[144:145], v[114:115] op_sel_hi:[0,1,1]
	v_pk_fma_f32 v[30:31], v[4:5], v[144:145], v[30:31] op_sel_hi:[0,1,1]
	ds_read_b128 v[142:145], v61 offset:8192
	s_waitcnt lgkmcnt(7)
	v_pk_fma_f32 v[66:67], v[224:225], v[146:147], v[66:67] op_sel:[1,0,0]
	v_pk_fma_f32 v[82:83], v[228:229], v[146:147], v[82:83] op_sel:[1,0,0]
	v_pk_fma_f32 v[100:101], v[0:1], v[146:147], v[100:101] op_sel:[1,0,0]
	v_pk_fma_f32 v[116:117], v[4:5], v[146:147], v[116:117] op_sel:[1,0,0]
	v_pk_fma_f32 v[68:69], v[224:225], v[148:149], v[68:69] op_sel:[1,0,0]
	v_pk_fma_f32 v[84:85], v[228:229], v[148:149], v[84:85] op_sel:[1,0,0]
	v_pk_fma_f32 v[102:103], v[0:1], v[148:149], v[102:103] op_sel:[1,0,0]
	v_pk_fma_f32 v[118:119], v[4:5], v[148:149], v[118:119] op_sel:[1,0,0]
	ds_read_b128 v[146:149], v58 offset:12288
	s_waitcnt lgkmcnt(7)
	v_pk_fma_f32 v[70:71], v[224:225], v[150:151], v[70:71] op_sel:[1,0,0]
	v_pk_fma_f32 v[86:87], v[228:229], v[150:151], v[86:87] op_sel:[1,0,0]
	v_pk_fma_f32 v[104:105], v[0:1], v[150:151], v[104:105] op_sel:[1,0,0]
	v_pk_fma_f32 v[120:121], v[4:5], v[150:151], v[120:121] op_sel:[1,0,0]
	v_pk_fma_f32 v[72:73], v[224:225], v[152:153], v[72:73] op_sel:[1,0,0]
	v_pk_fma_f32 v[88:89], v[228:229], v[152:153], v[88:89] op_sel:[1,0,0]
	v_pk_fma_f32 v[106:107], v[0:1], v[152:153], v[106:107] op_sel:[1,0,0]
	v_pk_fma_f32 v[122:123], v[4:5], v[152:153], v[122:123] op_sel:[1,0,0]
	ds_read_b128 v[150:153], v59 offset:12288
	s_waitcnt lgkmcnt(7)
	v_pk_fma_f32 v[74:75], v[224:225], v[154:155], v[74:75] op_sel:[1,0,0]
	v_pk_fma_f32 v[90:91], v[228:229], v[154:155], v[90:91] op_sel:[1,0,0]
	v_pk_fma_f32 v[108:109], v[0:1], v[154:155], v[108:109] op_sel:[1,0,0]
	v_pk_fma_f32 v[24:25], v[4:5], v[154:155], v[24:25] op_sel:[1,0,0]
	v_pk_fma_f32 v[76:77], v[224:225], v[156:157], v[76:77] op_sel:[1,0,0]
	v_pk_fma_f32 v[94:95], v[228:229], v[156:157], v[94:95] op_sel:[1,0,0]
	v_pk_fma_f32 v[110:111], v[0:1], v[156:157], v[110:111] op_sel:[1,0,0]
	v_pk_fma_f32 v[26:27], v[4:5], v[156:157], v[26:27] op_sel:[1,0,0]
	ds_read_b128 v[154:157], v60 offset:12288
	s_waitcnt lgkmcnt(7)
	v_pk_fma_f32 v[78:79], v[224:225], v[44:45], v[78:79] op_sel:[1,0,0]
	v_pk_fma_f32 v[96:97], v[228:229], v[44:45], v[96:97] op_sel:[1,0,0]
	v_pk_fma_f32 v[112:113], v[0:1], v[44:45], v[112:113] op_sel:[1,0,0]
	v_pk_fma_f32 v[28:29], v[4:5], v[44:45], v[28:29] op_sel:[1,0,0]
	v_pk_fma_f32 v[80:81], v[224:225], v[46:47], v[80:81] op_sel:[1,0,0]
	v_pk_fma_f32 v[98:99], v[228:229], v[46:47], v[98:99] op_sel:[1,0,0]
	v_pk_fma_f32 v[114:115], v[0:1], v[46:47], v[114:115] op_sel:[1,0,0]
	v_pk_fma_f32 v[30:31], v[4:5], v[46:47], v[30:31] op_sel:[1,0,0]
	ds_read_b128 v[44:47], v61 offset:12288
	s_waitcnt lgkmcnt(7)
	v_pk_fma_f32 v[66:67], v[226:227], v[130:131], v[66:67] op_sel_hi:[0,1,1]
	v_pk_fma_f32 v[82:83], v[230:231], v[130:131], v[82:83] op_sel_hi:[0,1,1]
	v_pk_fma_f32 v[100:101], v[2:3], v[130:131], v[100:101] op_sel_hi:[0,1,1]
	v_pk_fma_f32 v[116:117], v[6:7], v[130:131], v[116:117] op_sel_hi:[0,1,1]
	v_pk_fma_f32 v[68:69], v[226:227], v[132:133], v[68:69] op_sel_hi:[0,1,1]
	v_pk_fma_f32 v[84:85], v[230:231], v[132:133], v[84:85] op_sel_hi:[0,1,1]
	v_pk_fma_f32 v[102:103], v[2:3], v[132:133], v[102:103] op_sel_hi:[0,1,1]
	v_pk_fma_f32 v[118:119], v[6:7], v[132:133], v[118:119] op_sel_hi:[0,1,1]
	ds_read_b128 v[130:133], v58 offset:16384
	s_waitcnt lgkmcnt(7)
	v_pk_fma_f32 v[70:71], v[226:227], v[134:135], v[70:71] op_sel_hi:[0,1,1]
	v_pk_fma_f32 v[86:87], v[230:231], v[134:135], v[86:87] op_sel_hi:[0,1,1]
	v_pk_fma_f32 v[104:105], v[2:3], v[134:135], v[104:105] op_sel_hi:[0,1,1]
	v_pk_fma_f32 v[120:121], v[6:7], v[134:135], v[120:121] op_sel_hi:[0,1,1]
	v_pk_fma_f32 v[72:73], v[226:227], v[136:137], v[72:73] op_sel_hi:[0,1,1]
	v_pk_fma_f32 v[88:89], v[230:231], v[136:137], v[88:89] op_sel_hi:[0,1,1]
	v_pk_fma_f32 v[106:107], v[2:3], v[136:137], v[106:107] op_sel_hi:[0,1,1]
	v_pk_fma_f32 v[122:123], v[6:7], v[136:137], v[122:123] op_sel_hi:[0,1,1]
	ds_read_b128 v[134:137], v59 offset:16384
	s_waitcnt lgkmcnt(7)
	v_pk_fma_f32 v[74:75], v[226:227], v[138:139], v[74:75] op_sel_hi:[0,1,1]
	v_pk_fma_f32 v[90:91], v[230:231], v[138:139], v[90:91] op_sel_hi:[0,1,1]
	v_pk_fma_f32 v[108:109], v[2:3], v[138:139], v[108:109] op_sel_hi:[0,1,1]
	v_pk_fma_f32 v[24:25], v[6:7], v[138:139], v[24:25] op_sel_hi:[0,1,1]
	v_pk_fma_f32 v[76:77], v[226:227], v[140:141], v[76:77] op_sel_hi:[0,1,1]
	v_pk_fma_f32 v[94:95], v[230:231], v[140:141], v[94:95] op_sel_hi:[0,1,1]
	v_pk_fma_f32 v[110:111], v[2:3], v[140:141], v[110:111] op_sel_hi:[0,1,1]
	v_pk_fma_f32 v[26:27], v[6:7], v[140:141], v[26:27] op_sel_hi:[0,1,1]
	ds_read_b128 v[138:141], v60 offset:16384
	s_waitcnt lgkmcnt(7)
	v_pk_fma_f32 v[78:79], v[226:227], v[142:143], v[78:79] op_sel_hi:[0,1,1]
	v_pk_fma_f32 v[96:97], v[230:231], v[142:143], v[96:97] op_sel_hi:[0,1,1]
	v_pk_fma_f32 v[112:113], v[2:3], v[142:143], v[112:113] op_sel_hi:[0,1,1]
	v_pk_fma_f32 v[28:29], v[6:7], v[142:143], v[28:29] op_sel_hi:[0,1,1]
	v_pk_fma_f32 v[80:81], v[226:227], v[144:145], v[80:81] op_sel_hi:[0,1,1]
	v_pk_fma_f32 v[98:99], v[230:231], v[144:145], v[98:99] op_sel_hi:[0,1,1]
	v_pk_fma_f32 v[114:115], v[2:3], v[144:145], v[114:115] op_sel_hi:[0,1,1]
	v_pk_fma_f32 v[30:31], v[6:7], v[144:145], v[30:31] op_sel_hi:[0,1,1]
	ds_read_b128 v[142:145], v61 offset:16384
	s_waitcnt lgkmcnt(7)
	v_pk_fma_f32 v[66:67], v[226:227], v[146:147], v[66:67] op_sel:[1,0,0]
	v_pk_fma_f32 v[82:83], v[230:231], v[146:147], v[82:83] op_sel:[1,0,0]
	v_pk_fma_f32 v[100:101], v[2:3], v[146:147], v[100:101] op_sel:[1,0,0]
	v_pk_fma_f32 v[116:117], v[6:7], v[146:147], v[116:117] op_sel:[1,0,0]
	v_pk_fma_f32 v[68:69], v[226:227], v[148:149], v[68:69] op_sel:[1,0,0]
	v_pk_fma_f32 v[84:85], v[230:231], v[148:149], v[84:85] op_sel:[1,0,0]
	v_pk_fma_f32 v[102:103], v[2:3], v[148:149], v[102:103] op_sel:[1,0,0]
	v_pk_fma_f32 v[118:119], v[6:7], v[148:149], v[118:119] op_sel:[1,0,0]
	ds_read_b128 v[146:149], v58 offset:20480
	s_waitcnt lgkmcnt(7)
	v_pk_fma_f32 v[70:71], v[226:227], v[150:151], v[70:71] op_sel:[1,0,0]
	v_pk_fma_f32 v[86:87], v[230:231], v[150:151], v[86:87] op_sel:[1,0,0]
	v_pk_fma_f32 v[104:105], v[2:3], v[150:151], v[104:105] op_sel:[1,0,0]
	v_pk_fma_f32 v[120:121], v[6:7], v[150:151], v[120:121] op_sel:[1,0,0]
	v_pk_fma_f32 v[72:73], v[226:227], v[152:153], v[72:73] op_sel:[1,0,0]
	v_pk_fma_f32 v[88:89], v[230:231], v[152:153], v[88:89] op_sel:[1,0,0]
	v_pk_fma_f32 v[106:107], v[2:3], v[152:153], v[106:107] op_sel:[1,0,0]
	v_pk_fma_f32 v[122:123], v[6:7], v[152:153], v[122:123] op_sel:[1,0,0]
	ds_read_b128 v[150:153], v59 offset:20480
	s_waitcnt lgkmcnt(7)
	v_pk_fma_f32 v[74:75], v[226:227], v[154:155], v[74:75] op_sel:[1,0,0]
	v_pk_fma_f32 v[90:91], v[230:231], v[154:155], v[90:91] op_sel:[1,0,0]
	v_pk_fma_f32 v[108:109], v[2:3], v[154:155], v[108:109] op_sel:[1,0,0]
	v_pk_fma_f32 v[24:25], v[6:7], v[154:155], v[24:25] op_sel:[1,0,0]
	v_pk_fma_f32 v[76:77], v[226:227], v[156:157], v[76:77] op_sel:[1,0,0]
	v_pk_fma_f32 v[94:95], v[230:231], v[156:157], v[94:95] op_sel:[1,0,0]
	v_pk_fma_f32 v[110:111], v[2:3], v[156:157], v[110:111] op_sel:[1,0,0]
	v_pk_fma_f32 v[26:27], v[6:7], v[156:157], v[26:27] op_sel:[1,0,0]
	ds_read_b128 v[154:157], v60 offset:20480
	s_waitcnt lgkmcnt(7)
	v_pk_fma_f32 v[78:79], v[226:227], v[44:45], v[78:79] op_sel:[1,0,0]
	v_pk_fma_f32 v[96:97], v[230:231], v[44:45], v[96:97] op_sel:[1,0,0]
	v_pk_fma_f32 v[112:113], v[2:3], v[44:45], v[112:113] op_sel:[1,0,0]
	v_pk_fma_f32 v[28:29], v[6:7], v[44:45], v[28:29] op_sel:[1,0,0]
	v_pk_fma_f32 v[80:81], v[226:227], v[46:47], v[80:81] op_sel:[1,0,0]
	v_pk_fma_f32 v[98:99], v[230:231], v[46:47], v[98:99] op_sel:[1,0,0]
	v_pk_fma_f32 v[114:115], v[2:3], v[46:47], v[114:115] op_sel:[1,0,0]
	v_pk_fma_f32 v[30:31], v[6:7], v[46:47], v[30:31] op_sel:[1,0,0]
	ds_read_b128 v[44:47], v61 offset:20480
	s_waitcnt vmcnt(27)
	v_cvt_pk_bf16_f32 v244, v160, v161
	v_cvt_pk_bf16_f32 v245, v162, v163
	global_store_dwordx2 v[14:15], v[244:245], off offset:2560
	v_pk_mul_f32 v[22:23], v[160:161], v[160:161]
	v_pk_fma_f32 v[22:23], v[162:163], v[162:163], v[22:23]
	v_add_f32_e32 v22, v22, v23
	v_add_f32_e32 v240, v240, v22
	s_waitcnt vmcnt(27)
	v_cvt_pk_bf16_f32 v246, v164, v165
	v_cvt_pk_bf16_f32 v247, v166, v167
	global_store_dwordx2 v[16:17], v[246:247], off offset:2560
	v_pk_mul_f32 v[22:23], v[164:165], v[164:165]
	v_pk_fma_f32 v[22:23], v[166:167], v[166:167], v[22:23]
	v_add_f32_e32 v22, v22, v23
	v_add_f32_e32 v241, v241, v22
	s_waitcnt vmcnt(27)
	v_cvt_pk_bf16_f32 v248, v168, v169
	v_cvt_pk_bf16_f32 v249, v170, v171
	global_store_dwordx2 v[18:19], v[248:249], off offset:2560
	v_pk_mul_f32 v[22:23], v[168:169], v[168:169]
	v_pk_fma_f32 v[22:23], v[170:171], v[170:171], v[22:23]
	v_add_f32_e32 v22, v22, v23
	v_add_f32_e32 v242, v242, v22
	s_waitcnt vmcnt(27)
	v_cvt_pk_bf16_f32 v232, v172, v173
	v_cvt_pk_bf16_f32 v233, v174, v175
	global_store_dwordx2 v[20:21], v[232:233], off offset:2560
	v_pk_mul_f32 v[22:23], v[172:173], v[172:173]
	v_pk_fma_f32 v[22:23], v[174:175], v[174:175], v[22:23]
	v_add_f32_e32 v22, v22, v23
	v_add_f32_e32 v243, v243, v22
	s_waitcnt lgkmcnt(7)
	v_pk_fma_f32 v[66:67], v[160:161], v[130:131], v[66:67] op_sel_hi:[0,1,1]
	v_pk_fma_f32 v[82:83], v[164:165], v[130:131], v[82:83] op_sel_hi:[0,1,1]
	v_pk_fma_f32 v[100:101], v[168:169], v[130:131], v[100:101] op_sel_hi:[0,1,1]
	v_pk_fma_f32 v[116:117], v[172:173], v[130:131], v[116:117] op_sel_hi:[0,1,1]
	v_pk_fma_f32 v[68:69], v[160:161], v[132:133], v[68:69] op_sel_hi:[0,1,1]
	v_pk_fma_f32 v[84:85], v[164:165], v[132:133], v[84:85] op_sel_hi:[0,1,1]
	v_pk_fma_f32 v[102:103], v[168:169], v[132:133], v[102:103] op_sel_hi:[0,1,1]
	v_pk_fma_f32 v[118:119], v[172:173], v[132:133], v[118:119] op_sel_hi:[0,1,1]
	ds_read_b128 v[130:133], v58 offset:24576
	s_waitcnt lgkmcnt(7)
	v_pk_fma_f32 v[70:71], v[160:161], v[134:135], v[70:71] op_sel_hi:[0,1,1]
	v_pk_fma_f32 v[86:87], v[164:165], v[134:135], v[86:87] op_sel_hi:[0,1,1]
	v_pk_fma_f32 v[104:105], v[168:169], v[134:135], v[104:105] op_sel_hi:[0,1,1]
	v_pk_fma_f32 v[120:121], v[172:173], v[134:135], v[120:121] op_sel_hi:[0,1,1]
	v_pk_fma_f32 v[72:73], v[160:161], v[136:137], v[72:73] op_sel_hi:[0,1,1]
	v_pk_fma_f32 v[88:89], v[164:165], v[136:137], v[88:89] op_sel_hi:[0,1,1]
	v_pk_fma_f32 v[106:107], v[168:169], v[136:137], v[106:107] op_sel_hi:[0,1,1]
	v_pk_fma_f32 v[122:123], v[172:173], v[136:137], v[122:123] op_sel_hi:[0,1,1]
	ds_read_b128 v[134:137], v59 offset:24576
	s_waitcnt lgkmcnt(7)
	v_pk_fma_f32 v[74:75], v[160:161], v[138:139], v[74:75] op_sel_hi:[0,1,1]
	v_pk_fma_f32 v[90:91], v[164:165], v[138:139], v[90:91] op_sel_hi:[0,1,1]
	v_pk_fma_f32 v[108:109], v[168:169], v[138:139], v[108:109] op_sel_hi:[0,1,1]
	v_pk_fma_f32 v[24:25], v[172:173], v[138:139], v[24:25] op_sel_hi:[0,1,1]
	v_pk_fma_f32 v[76:77], v[160:161], v[140:141], v[76:77] op_sel_hi:[0,1,1]
	v_pk_fma_f32 v[94:95], v[164:165], v[140:141], v[94:95] op_sel_hi:[0,1,1]
	v_pk_fma_f32 v[110:111], v[168:169], v[140:141], v[110:111] op_sel_hi:[0,1,1]
	v_pk_fma_f32 v[26:27], v[172:173], v[140:141], v[26:27] op_sel_hi:[0,1,1]
	ds_read_b128 v[138:141], v60 offset:24576
	s_waitcnt lgkmcnt(7)
	v_pk_fma_f32 v[78:79], v[160:161], v[142:143], v[78:79] op_sel_hi:[0,1,1]
	v_pk_fma_f32 v[96:97], v[164:165], v[142:143], v[96:97] op_sel_hi:[0,1,1]
	v_pk_fma_f32 v[112:113], v[168:169], v[142:143], v[112:113] op_sel_hi:[0,1,1]
	v_pk_fma_f32 v[28:29], v[172:173], v[142:143], v[28:29] op_sel_hi:[0,1,1]
	v_pk_fma_f32 v[80:81], v[160:161], v[144:145], v[80:81] op_sel_hi:[0,1,1]
	v_pk_fma_f32 v[98:99], v[164:165], v[144:145], v[98:99] op_sel_hi:[0,1,1]
	v_pk_fma_f32 v[114:115], v[168:169], v[144:145], v[114:115] op_sel_hi:[0,1,1]
	v_pk_fma_f32 v[30:31], v[172:173], v[144:145], v[30:31] op_sel_hi:[0,1,1]
	ds_read_b128 v[142:145], v61 offset:24576
	s_waitcnt lgkmcnt(7)
	v_pk_fma_f32 v[66:67], v[160:161], v[146:147], v[66:67] op_sel:[1,0,0]
	v_pk_fma_f32 v[82:83], v[164:165], v[146:147], v[82:83] op_sel:[1,0,0]
	v_pk_fma_f32 v[100:101], v[168:169], v[146:147], v[100:101] op_sel:[1,0,0]
	v_pk_fma_f32 v[116:117], v[172:173], v[146:147], v[116:117] op_sel:[1,0,0]
	v_pk_fma_f32 v[68:69], v[160:161], v[148:149], v[68:69] op_sel:[1,0,0]
	v_pk_fma_f32 v[84:85], v[164:165], v[148:149], v[84:85] op_sel:[1,0,0]
	v_pk_fma_f32 v[102:103], v[168:169], v[148:149], v[102:103] op_sel:[1,0,0]
	v_pk_fma_f32 v[118:119], v[172:173], v[148:149], v[118:119] op_sel:[1,0,0]
	ds_read_b128 v[146:149], v58 offset:28672
	s_waitcnt lgkmcnt(7)
	v_pk_fma_f32 v[70:71], v[160:161], v[150:151], v[70:71] op_sel:[1,0,0]
	v_pk_fma_f32 v[86:87], v[164:165], v[150:151], v[86:87] op_sel:[1,0,0]
	v_pk_fma_f32 v[104:105], v[168:169], v[150:151], v[104:105] op_sel:[1,0,0]
	v_pk_fma_f32 v[120:121], v[172:173], v[150:151], v[120:121] op_sel:[1,0,0]
	v_pk_fma_f32 v[72:73], v[160:161], v[152:153], v[72:73] op_sel:[1,0,0]
	v_pk_fma_f32 v[88:89], v[164:165], v[152:153], v[88:89] op_sel:[1,0,0]
	v_pk_fma_f32 v[106:107], v[168:169], v[152:153], v[106:107] op_sel:[1,0,0]
	v_pk_fma_f32 v[122:123], v[172:173], v[152:153], v[122:123] op_sel:[1,0,0]
	ds_read_b128 v[150:153], v59 offset:28672
	s_waitcnt lgkmcnt(7)
	v_pk_fma_f32 v[74:75], v[160:161], v[154:155], v[74:75] op_sel:[1,0,0]
	v_pk_fma_f32 v[90:91], v[164:165], v[154:155], v[90:91] op_sel:[1,0,0]
	v_pk_fma_f32 v[108:109], v[168:169], v[154:155], v[108:109] op_sel:[1,0,0]
	v_pk_fma_f32 v[24:25], v[172:173], v[154:155], v[24:25] op_sel:[1,0,0]
	v_pk_fma_f32 v[76:77], v[160:161], v[156:157], v[76:77] op_sel:[1,0,0]
	v_pk_fma_f32 v[94:95], v[164:165], v[156:157], v[94:95] op_sel:[1,0,0]
	v_pk_fma_f32 v[110:111], v[168:169], v[156:157], v[110:111] op_sel:[1,0,0]
	v_pk_fma_f32 v[26:27], v[172:173], v[156:157], v[26:27] op_sel:[1,0,0]
	ds_read_b128 v[154:157], v60 offset:28672
	s_waitcnt lgkmcnt(7)
	v_pk_fma_f32 v[78:79], v[160:161], v[44:45], v[78:79] op_sel:[1,0,0]
	v_pk_fma_f32 v[96:97], v[164:165], v[44:45], v[96:97] op_sel:[1,0,0]
	v_pk_fma_f32 v[112:113], v[168:169], v[44:45], v[112:113] op_sel:[1,0,0]
	v_pk_fma_f32 v[28:29], v[172:173], v[44:45], v[28:29] op_sel:[1,0,0]
	v_pk_fma_f32 v[80:81], v[160:161], v[46:47], v[80:81] op_sel:[1,0,0]
	v_pk_fma_f32 v[98:99], v[164:165], v[46:47], v[98:99] op_sel:[1,0,0]
	v_pk_fma_f32 v[114:115], v[168:169], v[46:47], v[114:115] op_sel:[1,0,0]
	v_pk_fma_f32 v[30:31], v[172:173], v[46:47], v[30:31] op_sel:[1,0,0]
	ds_read_b128 v[44:47], v61 offset:28672
	s_waitcnt lgkmcnt(7)
	v_pk_fma_f32 v[66:67], v[162:163], v[130:131], v[66:67] op_sel_hi:[0,1,1]
	v_pk_fma_f32 v[82:83], v[166:167], v[130:131], v[82:83] op_sel_hi:[0,1,1]
	v_pk_fma_f32 v[100:101], v[170:171], v[130:131], v[100:101] op_sel_hi:[0,1,1]
	v_pk_fma_f32 v[116:117], v[174:175], v[130:131], v[116:117] op_sel_hi:[0,1,1]
	v_pk_fma_f32 v[68:69], v[162:163], v[132:133], v[68:69] op_sel_hi:[0,1,1]
	v_pk_fma_f32 v[84:85], v[166:167], v[132:133], v[84:85] op_sel_hi:[0,1,1]
	v_pk_fma_f32 v[102:103], v[170:171], v[132:133], v[102:103] op_sel_hi:[0,1,1]
	v_pk_fma_f32 v[118:119], v[174:175], v[132:133], v[118:119] op_sel_hi:[0,1,1]
	ds_read_b128 v[130:133], v58 offset:32768
	s_waitcnt lgkmcnt(7)
	v_pk_fma_f32 v[70:71], v[162:163], v[134:135], v[70:71] op_sel_hi:[0,1,1]
	v_pk_fma_f32 v[86:87], v[166:167], v[134:135], v[86:87] op_sel_hi:[0,1,1]
	v_pk_fma_f32 v[104:105], v[170:171], v[134:135], v[104:105] op_sel_hi:[0,1,1]
	v_pk_fma_f32 v[120:121], v[174:175], v[134:135], v[120:121] op_sel_hi:[0,1,1]
	v_pk_fma_f32 v[72:73], v[162:163], v[136:137], v[72:73] op_sel_hi:[0,1,1]
	v_pk_fma_f32 v[88:89], v[166:167], v[136:137], v[88:89] op_sel_hi:[0,1,1]
	v_pk_fma_f32 v[106:107], v[170:171], v[136:137], v[106:107] op_sel_hi:[0,1,1]
	v_pk_fma_f32 v[122:123], v[174:175], v[136:137], v[122:123] op_sel_hi:[0,1,1]
	ds_read_b128 v[134:137], v59 offset:32768
	s_waitcnt lgkmcnt(7)
	v_pk_fma_f32 v[74:75], v[162:163], v[138:139], v[74:75] op_sel_hi:[0,1,1]
	v_pk_fma_f32 v[90:91], v[166:167], v[138:139], v[90:91] op_sel_hi:[0,1,1]
	v_pk_fma_f32 v[108:109], v[170:171], v[138:139], v[108:109] op_sel_hi:[0,1,1]
	v_pk_fma_f32 v[24:25], v[174:175], v[138:139], v[24:25] op_sel_hi:[0,1,1]
	v_pk_fma_f32 v[76:77], v[162:163], v[140:141], v[76:77] op_sel_hi:[0,1,1]
	v_pk_fma_f32 v[94:95], v[166:167], v[140:141], v[94:95] op_sel_hi:[0,1,1]
	v_pk_fma_f32 v[110:111], v[170:171], v[140:141], v[110:111] op_sel_hi:[0,1,1]
	v_pk_fma_f32 v[26:27], v[174:175], v[140:141], v[26:27] op_sel_hi:[0,1,1]
	ds_read_b128 v[138:141], v60 offset:32768
	s_waitcnt lgkmcnt(7)
	v_pk_fma_f32 v[78:79], v[162:163], v[142:143], v[78:79] op_sel_hi:[0,1,1]
	v_pk_fma_f32 v[96:97], v[166:167], v[142:143], v[96:97] op_sel_hi:[0,1,1]
	v_pk_fma_f32 v[112:113], v[170:171], v[142:143], v[112:113] op_sel_hi:[0,1,1]
	v_pk_fma_f32 v[28:29], v[174:175], v[142:143], v[28:29] op_sel_hi:[0,1,1]
	v_pk_fma_f32 v[80:81], v[162:163], v[144:145], v[80:81] op_sel_hi:[0,1,1]
	v_pk_fma_f32 v[98:99], v[166:167], v[144:145], v[98:99] op_sel_hi:[0,1,1]
	v_pk_fma_f32 v[114:115], v[170:171], v[144:145], v[114:115] op_sel_hi:[0,1,1]
	v_pk_fma_f32 v[30:31], v[174:175], v[144:145], v[30:31] op_sel_hi:[0,1,1]
	ds_read_b128 v[142:145], v61 offset:32768
	s_waitcnt lgkmcnt(7)
	v_pk_fma_f32 v[66:67], v[162:163], v[146:147], v[66:67] op_sel:[1,0,0]
	v_pk_fma_f32 v[82:83], v[166:167], v[146:147], v[82:83] op_sel:[1,0,0]
	v_pk_fma_f32 v[100:101], v[170:171], v[146:147], v[100:101] op_sel:[1,0,0]
	v_pk_fma_f32 v[116:117], v[174:175], v[146:147], v[116:117] op_sel:[1,0,0]
	v_pk_fma_f32 v[68:69], v[162:163], v[148:149], v[68:69] op_sel:[1,0,0]
	v_pk_fma_f32 v[84:85], v[166:167], v[148:149], v[84:85] op_sel:[1,0,0]
	v_pk_fma_f32 v[102:103], v[170:171], v[148:149], v[102:103] op_sel:[1,0,0]
	v_pk_fma_f32 v[118:119], v[174:175], v[148:149], v[118:119] op_sel:[1,0,0]
	ds_read_b128 v[146:149], v58 offset:36864
	s_waitcnt lgkmcnt(7)
	v_pk_fma_f32 v[70:71], v[162:163], v[150:151], v[70:71] op_sel:[1,0,0]
	v_pk_fma_f32 v[86:87], v[166:167], v[150:151], v[86:87] op_sel:[1,0,0]
	v_pk_fma_f32 v[104:105], v[170:171], v[150:151], v[104:105] op_sel:[1,0,0]
	v_pk_fma_f32 v[120:121], v[174:175], v[150:151], v[120:121] op_sel:[1,0,0]
	v_pk_fma_f32 v[72:73], v[162:163], v[152:153], v[72:73] op_sel:[1,0,0]
	v_pk_fma_f32 v[88:89], v[166:167], v[152:153], v[88:89] op_sel:[1,0,0]
	v_pk_fma_f32 v[106:107], v[170:171], v[152:153], v[106:107] op_sel:[1,0,0]
	v_pk_fma_f32 v[122:123], v[174:175], v[152:153], v[122:123] op_sel:[1,0,0]
	ds_read_b128 v[150:153], v59 offset:36864
	s_waitcnt lgkmcnt(7)
	v_pk_fma_f32 v[74:75], v[162:163], v[154:155], v[74:75] op_sel:[1,0,0]
	v_pk_fma_f32 v[90:91], v[166:167], v[154:155], v[90:91] op_sel:[1,0,0]
	v_pk_fma_f32 v[108:109], v[170:171], v[154:155], v[108:109] op_sel:[1,0,0]
	v_pk_fma_f32 v[24:25], v[174:175], v[154:155], v[24:25] op_sel:[1,0,0]
	v_pk_fma_f32 v[76:77], v[162:163], v[156:157], v[76:77] op_sel:[1,0,0]
	v_pk_fma_f32 v[94:95], v[166:167], v[156:157], v[94:95] op_sel:[1,0,0]
	v_pk_fma_f32 v[110:111], v[170:171], v[156:157], v[110:111] op_sel:[1,0,0]
	v_pk_fma_f32 v[26:27], v[174:175], v[156:157], v[26:27] op_sel:[1,0,0]
	ds_read_b128 v[154:157], v60 offset:36864
	s_waitcnt lgkmcnt(7)
	v_pk_fma_f32 v[78:79], v[162:163], v[44:45], v[78:79] op_sel:[1,0,0]
	v_pk_fma_f32 v[96:97], v[166:167], v[44:45], v[96:97] op_sel:[1,0,0]
	v_pk_fma_f32 v[112:113], v[170:171], v[44:45], v[112:113] op_sel:[1,0,0]
	v_pk_fma_f32 v[28:29], v[174:175], v[44:45], v[28:29] op_sel:[1,0,0]
	v_pk_fma_f32 v[80:81], v[162:163], v[46:47], v[80:81] op_sel:[1,0,0]
	v_pk_fma_f32 v[98:99], v[166:167], v[46:47], v[98:99] op_sel:[1,0,0]
	v_pk_fma_f32 v[114:115], v[170:171], v[46:47], v[114:115] op_sel:[1,0,0]
	v_pk_fma_f32 v[30:31], v[174:175], v[46:47], v[30:31] op_sel:[1,0,0]
	ds_read_b128 v[44:47], v61 offset:36864
	s_waitcnt vmcnt(23)
	v_cvt_pk_bf16_f32 v244, v176, v177
	v_cvt_pk_bf16_f32 v245, v178, v179
	global_store_dwordx2 v[14:15], v[244:245], off offset:3072
	v_pk_mul_f32 v[22:23], v[176:177], v[176:177]
	v_pk_fma_f32 v[22:23], v[178:179], v[178:179], v[22:23]
	v_add_f32_e32 v22, v22, v23
	v_add_f32_e32 v240, v240, v22
	s_waitcnt vmcnt(23)
	v_cvt_pk_bf16_f32 v246, v180, v181
	v_cvt_pk_bf16_f32 v247, v182, v183
	global_store_dwordx2 v[16:17], v[246:247], off offset:3072
	v_pk_mul_f32 v[22:23], v[180:181], v[180:181]
	v_pk_fma_f32 v[22:23], v[182:183], v[182:183], v[22:23]
	v_add_f32_e32 v22, v22, v23
	v_add_f32_e32 v241, v241, v22
	s_waitcnt vmcnt(23)
	v_cvt_pk_bf16_f32 v248, v184, v185
	v_cvt_pk_bf16_f32 v249, v186, v187
	global_store_dwordx2 v[18:19], v[248:249], off offset:3072
	v_pk_mul_f32 v[22:23], v[184:185], v[184:185]
	v_pk_fma_f32 v[22:23], v[186:187], v[186:187], v[22:23]
	v_add_f32_e32 v22, v22, v23
	v_add_f32_e32 v242, v242, v22
	s_waitcnt vmcnt(23)
	v_cvt_pk_bf16_f32 v232, v188, v189
	v_cvt_pk_bf16_f32 v233, v190, v191
	global_store_dwordx2 v[20:21], v[232:233], off offset:3072
	v_pk_mul_f32 v[22:23], v[188:189], v[188:189]
	v_pk_fma_f32 v[22:23], v[190:191], v[190:191], v[22:23]
	v_add_f32_e32 v22, v22, v23
	v_add_f32_e32 v243, v243, v22
	s_waitcnt lgkmcnt(7)
	v_pk_fma_f32 v[66:67], v[176:177], v[130:131], v[66:67] op_sel_hi:[0,1,1]
	v_pk_fma_f32 v[82:83], v[180:181], v[130:131], v[82:83] op_sel_hi:[0,1,1]
	v_pk_fma_f32 v[100:101], v[184:185], v[130:131], v[100:101] op_sel_hi:[0,1,1]
	v_pk_fma_f32 v[116:117], v[188:189], v[130:131], v[116:117] op_sel_hi:[0,1,1]
	v_pk_fma_f32 v[68:69], v[176:177], v[132:133], v[68:69] op_sel_hi:[0,1,1]
	v_pk_fma_f32 v[84:85], v[180:181], v[132:133], v[84:85] op_sel_hi:[0,1,1]
	v_pk_fma_f32 v[102:103], v[184:185], v[132:133], v[102:103] op_sel_hi:[0,1,1]
	v_pk_fma_f32 v[118:119], v[188:189], v[132:133], v[118:119] op_sel_hi:[0,1,1]
	ds_read_b128 v[130:133], v58 offset:40960
	s_waitcnt lgkmcnt(7)
	v_pk_fma_f32 v[70:71], v[176:177], v[134:135], v[70:71] op_sel_hi:[0,1,1]
	v_pk_fma_f32 v[86:87], v[180:181], v[134:135], v[86:87] op_sel_hi:[0,1,1]
	v_pk_fma_f32 v[104:105], v[184:185], v[134:135], v[104:105] op_sel_hi:[0,1,1]
	v_pk_fma_f32 v[120:121], v[188:189], v[134:135], v[120:121] op_sel_hi:[0,1,1]
	v_pk_fma_f32 v[72:73], v[176:177], v[136:137], v[72:73] op_sel_hi:[0,1,1]
	v_pk_fma_f32 v[88:89], v[180:181], v[136:137], v[88:89] op_sel_hi:[0,1,1]
	v_pk_fma_f32 v[106:107], v[184:185], v[136:137], v[106:107] op_sel_hi:[0,1,1]
	v_pk_fma_f32 v[122:123], v[188:189], v[136:137], v[122:123] op_sel_hi:[0,1,1]
	ds_read_b128 v[134:137], v59 offset:40960
	s_waitcnt lgkmcnt(7)
	v_pk_fma_f32 v[74:75], v[176:177], v[138:139], v[74:75] op_sel_hi:[0,1,1]
	v_pk_fma_f32 v[90:91], v[180:181], v[138:139], v[90:91] op_sel_hi:[0,1,1]
	v_pk_fma_f32 v[108:109], v[184:185], v[138:139], v[108:109] op_sel_hi:[0,1,1]
	v_pk_fma_f32 v[24:25], v[188:189], v[138:139], v[24:25] op_sel_hi:[0,1,1]
	v_pk_fma_f32 v[76:77], v[176:177], v[140:141], v[76:77] op_sel_hi:[0,1,1]
	v_pk_fma_f32 v[94:95], v[180:181], v[140:141], v[94:95] op_sel_hi:[0,1,1]
	v_pk_fma_f32 v[110:111], v[184:185], v[140:141], v[110:111] op_sel_hi:[0,1,1]
	v_pk_fma_f32 v[26:27], v[188:189], v[140:141], v[26:27] op_sel_hi:[0,1,1]
	ds_read_b128 v[138:141], v60 offset:40960
	s_waitcnt lgkmcnt(7)
	v_pk_fma_f32 v[78:79], v[176:177], v[142:143], v[78:79] op_sel_hi:[0,1,1]
	v_pk_fma_f32 v[96:97], v[180:181], v[142:143], v[96:97] op_sel_hi:[0,1,1]
	v_pk_fma_f32 v[112:113], v[184:185], v[142:143], v[112:113] op_sel_hi:[0,1,1]
	v_pk_fma_f32 v[28:29], v[188:189], v[142:143], v[28:29] op_sel_hi:[0,1,1]
	v_pk_fma_f32 v[80:81], v[176:177], v[144:145], v[80:81] op_sel_hi:[0,1,1]
	v_pk_fma_f32 v[98:99], v[180:181], v[144:145], v[98:99] op_sel_hi:[0,1,1]
	v_pk_fma_f32 v[114:115], v[184:185], v[144:145], v[114:115] op_sel_hi:[0,1,1]
	v_pk_fma_f32 v[30:31], v[188:189], v[144:145], v[30:31] op_sel_hi:[0,1,1]
	ds_read_b128 v[142:145], v61 offset:40960
	s_waitcnt lgkmcnt(7)
	v_pk_fma_f32 v[66:67], v[176:177], v[146:147], v[66:67] op_sel:[1,0,0]
	v_pk_fma_f32 v[82:83], v[180:181], v[146:147], v[82:83] op_sel:[1,0,0]
	v_pk_fma_f32 v[100:101], v[184:185], v[146:147], v[100:101] op_sel:[1,0,0]
	v_pk_fma_f32 v[116:117], v[188:189], v[146:147], v[116:117] op_sel:[1,0,0]
	v_pk_fma_f32 v[68:69], v[176:177], v[148:149], v[68:69] op_sel:[1,0,0]
	v_pk_fma_f32 v[84:85], v[180:181], v[148:149], v[84:85] op_sel:[1,0,0]
	v_pk_fma_f32 v[102:103], v[184:185], v[148:149], v[102:103] op_sel:[1,0,0]
	v_pk_fma_f32 v[118:119], v[188:189], v[148:149], v[118:119] op_sel:[1,0,0]
	ds_read_b128 v[146:149], v58 offset:45056
	s_waitcnt lgkmcnt(7)
	v_pk_fma_f32 v[70:71], v[176:177], v[150:151], v[70:71] op_sel:[1,0,0]
	v_pk_fma_f32 v[86:87], v[180:181], v[150:151], v[86:87] op_sel:[1,0,0]
	v_pk_fma_f32 v[104:105], v[184:185], v[150:151], v[104:105] op_sel:[1,0,0]
	v_pk_fma_f32 v[120:121], v[188:189], v[150:151], v[120:121] op_sel:[1,0,0]
	v_pk_fma_f32 v[72:73], v[176:177], v[152:153], v[72:73] op_sel:[1,0,0]
	v_pk_fma_f32 v[88:89], v[180:181], v[152:153], v[88:89] op_sel:[1,0,0]
	v_pk_fma_f32 v[106:107], v[184:185], v[152:153], v[106:107] op_sel:[1,0,0]
	v_pk_fma_f32 v[122:123], v[188:189], v[152:153], v[122:123] op_sel:[1,0,0]
	ds_read_b128 v[150:153], v59 offset:45056
	s_waitcnt lgkmcnt(7)
	v_pk_fma_f32 v[74:75], v[176:177], v[154:155], v[74:75] op_sel:[1,0,0]
	v_pk_fma_f32 v[90:91], v[180:181], v[154:155], v[90:91] op_sel:[1,0,0]
	v_pk_fma_f32 v[108:109], v[184:185], v[154:155], v[108:109] op_sel:[1,0,0]
	v_pk_fma_f32 v[24:25], v[188:189], v[154:155], v[24:25] op_sel:[1,0,0]
	v_pk_fma_f32 v[76:77], v[176:177], v[156:157], v[76:77] op_sel:[1,0,0]
	v_pk_fma_f32 v[94:95], v[180:181], v[156:157], v[94:95] op_sel:[1,0,0]
	v_pk_fma_f32 v[110:111], v[184:185], v[156:157], v[110:111] op_sel:[1,0,0]
	v_pk_fma_f32 v[26:27], v[188:189], v[156:157], v[26:27] op_sel:[1,0,0]
	ds_read_b128 v[154:157], v60 offset:45056
	s_waitcnt lgkmcnt(7)
	v_pk_fma_f32 v[78:79], v[176:177], v[44:45], v[78:79] op_sel:[1,0,0]
	v_pk_fma_f32 v[96:97], v[180:181], v[44:45], v[96:97] op_sel:[1,0,0]
	v_pk_fma_f32 v[112:113], v[184:185], v[44:45], v[112:113] op_sel:[1,0,0]
	v_pk_fma_f32 v[28:29], v[188:189], v[44:45], v[28:29] op_sel:[1,0,0]
	v_pk_fma_f32 v[80:81], v[176:177], v[46:47], v[80:81] op_sel:[1,0,0]
	v_pk_fma_f32 v[98:99], v[180:181], v[46:47], v[98:99] op_sel:[1,0,0]
	v_pk_fma_f32 v[114:115], v[184:185], v[46:47], v[114:115] op_sel:[1,0,0]
	v_pk_fma_f32 v[30:31], v[188:189], v[46:47], v[30:31] op_sel:[1,0,0]
	ds_read_b128 v[44:47], v61 offset:45056
	s_waitcnt lgkmcnt(7)
	v_pk_fma_f32 v[66:67], v[178:179], v[130:131], v[66:67] op_sel_hi:[0,1,1]
	v_pk_fma_f32 v[82:83], v[182:183], v[130:131], v[82:83] op_sel_hi:[0,1,1]
	v_pk_fma_f32 v[100:101], v[186:187], v[130:131], v[100:101] op_sel_hi:[0,1,1]
	v_pk_fma_f32 v[116:117], v[190:191], v[130:131], v[116:117] op_sel_hi:[0,1,1]
	v_pk_fma_f32 v[68:69], v[178:179], v[132:133], v[68:69] op_sel_hi:[0,1,1]
	v_pk_fma_f32 v[84:85], v[182:183], v[132:133], v[84:85] op_sel_hi:[0,1,1]
	v_pk_fma_f32 v[102:103], v[186:187], v[132:133], v[102:103] op_sel_hi:[0,1,1]
	v_pk_fma_f32 v[118:119], v[190:191], v[132:133], v[118:119] op_sel_hi:[0,1,1]
	ds_read_b128 v[130:133], v58 offset:49152
	s_waitcnt lgkmcnt(7)
	v_pk_fma_f32 v[70:71], v[178:179], v[134:135], v[70:71] op_sel_hi:[0,1,1]
	v_pk_fma_f32 v[86:87], v[182:183], v[134:135], v[86:87] op_sel_hi:[0,1,1]
	v_pk_fma_f32 v[104:105], v[186:187], v[134:135], v[104:105] op_sel_hi:[0,1,1]
	v_pk_fma_f32 v[120:121], v[190:191], v[134:135], v[120:121] op_sel_hi:[0,1,1]
	v_pk_fma_f32 v[72:73], v[178:179], v[136:137], v[72:73] op_sel_hi:[0,1,1]
	v_pk_fma_f32 v[88:89], v[182:183], v[136:137], v[88:89] op_sel_hi:[0,1,1]
	v_pk_fma_f32 v[106:107], v[186:187], v[136:137], v[106:107] op_sel_hi:[0,1,1]
	v_pk_fma_f32 v[122:123], v[190:191], v[136:137], v[122:123] op_sel_hi:[0,1,1]
	ds_read_b128 v[134:137], v59 offset:49152
	s_waitcnt lgkmcnt(7)
	v_pk_fma_f32 v[74:75], v[178:179], v[138:139], v[74:75] op_sel_hi:[0,1,1]
	v_pk_fma_f32 v[90:91], v[182:183], v[138:139], v[90:91] op_sel_hi:[0,1,1]
	v_pk_fma_f32 v[108:109], v[186:187], v[138:139], v[108:109] op_sel_hi:[0,1,1]
	v_pk_fma_f32 v[24:25], v[190:191], v[138:139], v[24:25] op_sel_hi:[0,1,1]
	v_pk_fma_f32 v[76:77], v[178:179], v[140:141], v[76:77] op_sel_hi:[0,1,1]
	v_pk_fma_f32 v[94:95], v[182:183], v[140:141], v[94:95] op_sel_hi:[0,1,1]
	v_pk_fma_f32 v[110:111], v[186:187], v[140:141], v[110:111] op_sel_hi:[0,1,1]
	v_pk_fma_f32 v[26:27], v[190:191], v[140:141], v[26:27] op_sel_hi:[0,1,1]
	ds_read_b128 v[138:141], v60 offset:49152
	s_waitcnt lgkmcnt(7)
	v_pk_fma_f32 v[78:79], v[178:179], v[142:143], v[78:79] op_sel_hi:[0,1,1]
	v_pk_fma_f32 v[96:97], v[182:183], v[142:143], v[96:97] op_sel_hi:[0,1,1]
	v_pk_fma_f32 v[112:113], v[186:187], v[142:143], v[112:113] op_sel_hi:[0,1,1]
	v_pk_fma_f32 v[28:29], v[190:191], v[142:143], v[28:29] op_sel_hi:[0,1,1]
	v_pk_fma_f32 v[80:81], v[178:179], v[144:145], v[80:81] op_sel_hi:[0,1,1]
	v_pk_fma_f32 v[98:99], v[182:183], v[144:145], v[98:99] op_sel_hi:[0,1,1]
	v_pk_fma_f32 v[114:115], v[186:187], v[144:145], v[114:115] op_sel_hi:[0,1,1]
	v_pk_fma_f32 v[30:31], v[190:191], v[144:145], v[30:31] op_sel_hi:[0,1,1]
	ds_read_b128 v[142:145], v61 offset:49152
	s_waitcnt lgkmcnt(7)
	v_pk_fma_f32 v[66:67], v[178:179], v[146:147], v[66:67] op_sel:[1,0,0]
	v_pk_fma_f32 v[82:83], v[182:183], v[146:147], v[82:83] op_sel:[1,0,0]
	v_pk_fma_f32 v[100:101], v[186:187], v[146:147], v[100:101] op_sel:[1,0,0]
	v_pk_fma_f32 v[116:117], v[190:191], v[146:147], v[116:117] op_sel:[1,0,0]
	v_pk_fma_f32 v[68:69], v[178:179], v[148:149], v[68:69] op_sel:[1,0,0]
	v_pk_fma_f32 v[84:85], v[182:183], v[148:149], v[84:85] op_sel:[1,0,0]
	v_pk_fma_f32 v[102:103], v[186:187], v[148:149], v[102:103] op_sel:[1,0,0]
	v_pk_fma_f32 v[118:119], v[190:191], v[148:149], v[118:119] op_sel:[1,0,0]
	ds_read_b128 v[146:149], v58 offset:53248
	s_waitcnt lgkmcnt(7)
	v_pk_fma_f32 v[70:71], v[178:179], v[150:151], v[70:71] op_sel:[1,0,0]
	v_pk_fma_f32 v[86:87], v[182:183], v[150:151], v[86:87] op_sel:[1,0,0]
	v_pk_fma_f32 v[104:105], v[186:187], v[150:151], v[104:105] op_sel:[1,0,0]
	v_pk_fma_f32 v[120:121], v[190:191], v[150:151], v[120:121] op_sel:[1,0,0]
	v_pk_fma_f32 v[72:73], v[178:179], v[152:153], v[72:73] op_sel:[1,0,0]
	v_pk_fma_f32 v[88:89], v[182:183], v[152:153], v[88:89] op_sel:[1,0,0]
	v_pk_fma_f32 v[106:107], v[186:187], v[152:153], v[106:107] op_sel:[1,0,0]
	v_pk_fma_f32 v[122:123], v[190:191], v[152:153], v[122:123] op_sel:[1,0,0]
	ds_read_b128 v[150:153], v59 offset:53248
	s_waitcnt lgkmcnt(7)
	v_pk_fma_f32 v[74:75], v[178:179], v[154:155], v[74:75] op_sel:[1,0,0]
	v_pk_fma_f32 v[90:91], v[182:183], v[154:155], v[90:91] op_sel:[1,0,0]
	v_pk_fma_f32 v[108:109], v[186:187], v[154:155], v[108:109] op_sel:[1,0,0]
	v_pk_fma_f32 v[24:25], v[190:191], v[154:155], v[24:25] op_sel:[1,0,0]
	v_pk_fma_f32 v[76:77], v[178:179], v[156:157], v[76:77] op_sel:[1,0,0]
	v_pk_fma_f32 v[94:95], v[182:183], v[156:157], v[94:95] op_sel:[1,0,0]
	v_pk_fma_f32 v[110:111], v[186:187], v[156:157], v[110:111] op_sel:[1,0,0]
	v_pk_fma_f32 v[26:27], v[190:191], v[156:157], v[26:27] op_sel:[1,0,0]
	ds_read_b128 v[154:157], v60 offset:53248
	s_waitcnt lgkmcnt(7)
	v_pk_fma_f32 v[78:79], v[178:179], v[44:45], v[78:79] op_sel:[1,0,0]
	v_pk_fma_f32 v[96:97], v[182:183], v[44:45], v[96:97] op_sel:[1,0,0]
	v_pk_fma_f32 v[112:113], v[186:187], v[44:45], v[112:113] op_sel:[1,0,0]
	v_pk_fma_f32 v[28:29], v[190:191], v[44:45], v[28:29] op_sel:[1,0,0]
	v_pk_fma_f32 v[80:81], v[178:179], v[46:47], v[80:81] op_sel:[1,0,0]
	v_pk_fma_f32 v[98:99], v[182:183], v[46:47], v[98:99] op_sel:[1,0,0]
	v_pk_fma_f32 v[114:115], v[186:187], v[46:47], v[114:115] op_sel:[1,0,0]
	v_pk_fma_f32 v[30:31], v[190:191], v[46:47], v[30:31] op_sel:[1,0,0]
	ds_read_b128 v[44:47], v61 offset:53248
	s_waitcnt vmcnt(19)
	v_cvt_pk_bf16_f32 v244, v192, v193
	v_cvt_pk_bf16_f32 v245, v194, v195
	global_store_dwordx2 v[14:15], v[244:245], off offset:3584
	v_pk_mul_f32 v[22:23], v[192:193], v[192:193]
	v_pk_fma_f32 v[22:23], v[194:195], v[194:195], v[22:23]
	v_add_f32_e32 v22, v22, v23
	v_add_f32_e32 v240, v240, v22
	s_waitcnt vmcnt(19)
	v_cvt_pk_bf16_f32 v246, v196, v197
	v_cvt_pk_bf16_f32 v247, v198, v199
	global_store_dwordx2 v[16:17], v[246:247], off offset:3584
	v_pk_mul_f32 v[22:23], v[196:197], v[196:197]
	v_pk_fma_f32 v[22:23], v[198:199], v[198:199], v[22:23]
	v_add_f32_e32 v22, v22, v23
	v_add_f32_e32 v241, v241, v22
	s_waitcnt vmcnt(19)
	v_cvt_pk_bf16_f32 v248, v200, v201
	v_cvt_pk_bf16_f32 v249, v202, v203
	global_store_dwordx2 v[18:19], v[248:249], off offset:3584
	v_pk_mul_f32 v[22:23], v[200:201], v[200:201]
	v_pk_fma_f32 v[22:23], v[202:203], v[202:203], v[22:23]
	v_add_f32_e32 v22, v22, v23
	v_add_f32_e32 v242, v242, v22
	s_waitcnt vmcnt(19)
	v_cvt_pk_bf16_f32 v232, v204, v205
	v_cvt_pk_bf16_f32 v233, v206, v207
	global_store_dwordx2 v[20:21], v[232:233], off offset:3584
	v_pk_mul_f32 v[22:23], v[204:205], v[204:205]
	v_pk_fma_f32 v[22:23], v[206:207], v[206:207], v[22:23]
	v_add_f32_e32 v22, v22, v23
	v_add_f32_e32 v243, v243, v22
	s_waitcnt lgkmcnt(7)
	v_pk_fma_f32 v[66:67], v[192:193], v[130:131], v[66:67] op_sel_hi:[0,1,1]
	v_pk_fma_f32 v[82:83], v[196:197], v[130:131], v[82:83] op_sel_hi:[0,1,1]
	v_pk_fma_f32 v[100:101], v[200:201], v[130:131], v[100:101] op_sel_hi:[0,1,1]
	v_pk_fma_f32 v[116:117], v[204:205], v[130:131], v[116:117] op_sel_hi:[0,1,1]
	v_pk_fma_f32 v[68:69], v[192:193], v[132:133], v[68:69] op_sel_hi:[0,1,1]
	v_pk_fma_f32 v[84:85], v[196:197], v[132:133], v[84:85] op_sel_hi:[0,1,1]
	v_pk_fma_f32 v[102:103], v[200:201], v[132:133], v[102:103] op_sel_hi:[0,1,1]
	v_pk_fma_f32 v[118:119], v[204:205], v[132:133], v[118:119] op_sel_hi:[0,1,1]
	ds_read_b128 v[130:133], v58 offset:57344
	s_waitcnt lgkmcnt(7)
	v_pk_fma_f32 v[70:71], v[192:193], v[134:135], v[70:71] op_sel_hi:[0,1,1]
	v_pk_fma_f32 v[86:87], v[196:197], v[134:135], v[86:87] op_sel_hi:[0,1,1]
	v_pk_fma_f32 v[104:105], v[200:201], v[134:135], v[104:105] op_sel_hi:[0,1,1]
	v_pk_fma_f32 v[120:121], v[204:205], v[134:135], v[120:121] op_sel_hi:[0,1,1]
	v_pk_fma_f32 v[72:73], v[192:193], v[136:137], v[72:73] op_sel_hi:[0,1,1]
	v_pk_fma_f32 v[88:89], v[196:197], v[136:137], v[88:89] op_sel_hi:[0,1,1]
	v_pk_fma_f32 v[106:107], v[200:201], v[136:137], v[106:107] op_sel_hi:[0,1,1]
	v_pk_fma_f32 v[122:123], v[204:205], v[136:137], v[122:123] op_sel_hi:[0,1,1]
	ds_read_b128 v[134:137], v59 offset:57344
	s_waitcnt lgkmcnt(7)
	v_pk_fma_f32 v[74:75], v[192:193], v[138:139], v[74:75] op_sel_hi:[0,1,1]
	v_pk_fma_f32 v[90:91], v[196:197], v[138:139], v[90:91] op_sel_hi:[0,1,1]
	v_pk_fma_f32 v[108:109], v[200:201], v[138:139], v[108:109] op_sel_hi:[0,1,1]
	v_pk_fma_f32 v[24:25], v[204:205], v[138:139], v[24:25] op_sel_hi:[0,1,1]
	v_pk_fma_f32 v[76:77], v[192:193], v[140:141], v[76:77] op_sel_hi:[0,1,1]
	v_pk_fma_f32 v[94:95], v[196:197], v[140:141], v[94:95] op_sel_hi:[0,1,1]
	v_pk_fma_f32 v[110:111], v[200:201], v[140:141], v[110:111] op_sel_hi:[0,1,1]
	v_pk_fma_f32 v[26:27], v[204:205], v[140:141], v[26:27] op_sel_hi:[0,1,1]
	ds_read_b128 v[138:141], v60 offset:57344
	s_waitcnt lgkmcnt(7)
	v_pk_fma_f32 v[78:79], v[192:193], v[142:143], v[78:79] op_sel_hi:[0,1,1]
	v_pk_fma_f32 v[96:97], v[196:197], v[142:143], v[96:97] op_sel_hi:[0,1,1]
	v_pk_fma_f32 v[112:113], v[200:201], v[142:143], v[112:113] op_sel_hi:[0,1,1]
	v_pk_fma_f32 v[28:29], v[204:205], v[142:143], v[28:29] op_sel_hi:[0,1,1]
	v_pk_fma_f32 v[80:81], v[192:193], v[144:145], v[80:81] op_sel_hi:[0,1,1]
	v_pk_fma_f32 v[98:99], v[196:197], v[144:145], v[98:99] op_sel_hi:[0,1,1]
	v_pk_fma_f32 v[114:115], v[200:201], v[144:145], v[114:115] op_sel_hi:[0,1,1]
	v_pk_fma_f32 v[30:31], v[204:205], v[144:145], v[30:31] op_sel_hi:[0,1,1]
	ds_read_b128 v[142:145], v61 offset:57344
	s_waitcnt lgkmcnt(7)
	v_pk_fma_f32 v[66:67], v[192:193], v[146:147], v[66:67] op_sel:[1,0,0]
	v_pk_fma_f32 v[82:83], v[196:197], v[146:147], v[82:83] op_sel:[1,0,0]
	v_pk_fma_f32 v[100:101], v[200:201], v[146:147], v[100:101] op_sel:[1,0,0]
	v_pk_fma_f32 v[116:117], v[204:205], v[146:147], v[116:117] op_sel:[1,0,0]
	v_pk_fma_f32 v[68:69], v[192:193], v[148:149], v[68:69] op_sel:[1,0,0]
	v_pk_fma_f32 v[84:85], v[196:197], v[148:149], v[84:85] op_sel:[1,0,0]
	v_pk_fma_f32 v[102:103], v[200:201], v[148:149], v[102:103] op_sel:[1,0,0]
	v_pk_fma_f32 v[118:119], v[204:205], v[148:149], v[118:119] op_sel:[1,0,0]
	ds_read_b128 v[146:149], v58 offset:61440
	s_waitcnt lgkmcnt(7)
	v_pk_fma_f32 v[70:71], v[192:193], v[150:151], v[70:71] op_sel:[1,0,0]
	v_pk_fma_f32 v[86:87], v[196:197], v[150:151], v[86:87] op_sel:[1,0,0]
	v_pk_fma_f32 v[104:105], v[200:201], v[150:151], v[104:105] op_sel:[1,0,0]
	v_pk_fma_f32 v[120:121], v[204:205], v[150:151], v[120:121] op_sel:[1,0,0]
	v_pk_fma_f32 v[72:73], v[192:193], v[152:153], v[72:73] op_sel:[1,0,0]
	v_pk_fma_f32 v[88:89], v[196:197], v[152:153], v[88:89] op_sel:[1,0,0]
	v_pk_fma_f32 v[106:107], v[200:201], v[152:153], v[106:107] op_sel:[1,0,0]
	v_pk_fma_f32 v[122:123], v[204:205], v[152:153], v[122:123] op_sel:[1,0,0]
	ds_read_b128 v[150:153], v59 offset:61440
	s_waitcnt lgkmcnt(7)
	v_pk_fma_f32 v[74:75], v[192:193], v[154:155], v[74:75] op_sel:[1,0,0]
	v_pk_fma_f32 v[90:91], v[196:197], v[154:155], v[90:91] op_sel:[1,0,0]
	v_pk_fma_f32 v[108:109], v[200:201], v[154:155], v[108:109] op_sel:[1,0,0]
	v_pk_fma_f32 v[24:25], v[204:205], v[154:155], v[24:25] op_sel:[1,0,0]
	v_pk_fma_f32 v[76:77], v[192:193], v[156:157], v[76:77] op_sel:[1,0,0]
	v_pk_fma_f32 v[94:95], v[196:197], v[156:157], v[94:95] op_sel:[1,0,0]
	v_pk_fma_f32 v[110:111], v[200:201], v[156:157], v[110:111] op_sel:[1,0,0]
	v_pk_fma_f32 v[26:27], v[204:205], v[156:157], v[26:27] op_sel:[1,0,0]
	ds_read_b128 v[154:157], v60 offset:61440
	s_waitcnt lgkmcnt(7)
	v_pk_fma_f32 v[78:79], v[192:193], v[44:45], v[78:79] op_sel:[1,0,0]
	v_pk_fma_f32 v[96:97], v[196:197], v[44:45], v[96:97] op_sel:[1,0,0]
	v_pk_fma_f32 v[112:113], v[200:201], v[44:45], v[112:113] op_sel:[1,0,0]
	v_pk_fma_f32 v[28:29], v[204:205], v[44:45], v[28:29] op_sel:[1,0,0]
	v_pk_fma_f32 v[80:81], v[192:193], v[46:47], v[80:81] op_sel:[1,0,0]
	v_pk_fma_f32 v[98:99], v[196:197], v[46:47], v[98:99] op_sel:[1,0,0]
	v_pk_fma_f32 v[114:115], v[200:201], v[46:47], v[114:115] op_sel:[1,0,0]
	v_pk_fma_f32 v[30:31], v[204:205], v[46:47], v[30:31] op_sel:[1,0,0]
	ds_read_b128 v[44:47], v61 offset:61440
	s_waitcnt lgkmcnt(7)
	v_pk_fma_f32 v[66:67], v[194:195], v[130:131], v[66:67] op_sel_hi:[0,1,1]
	v_pk_fma_f32 v[82:83], v[198:199], v[130:131], v[82:83] op_sel_hi:[0,1,1]
	v_pk_fma_f32 v[100:101], v[202:203], v[130:131], v[100:101] op_sel_hi:[0,1,1]
	v_pk_fma_f32 v[116:117], v[206:207], v[130:131], v[116:117] op_sel_hi:[0,1,1]
	v_pk_fma_f32 v[68:69], v[194:195], v[132:133], v[68:69] op_sel_hi:[0,1,1]
	v_pk_fma_f32 v[84:85], v[198:199], v[132:133], v[84:85] op_sel_hi:[0,1,1]
	v_pk_fma_f32 v[102:103], v[202:203], v[132:133], v[102:103] op_sel_hi:[0,1,1]
	v_pk_fma_f32 v[118:119], v[206:207], v[132:133], v[118:119] op_sel_hi:[0,1,1]
	s_waitcnt lgkmcnt(6)
	v_pk_fma_f32 v[70:71], v[194:195], v[134:135], v[70:71] op_sel_hi:[0,1,1]
	v_pk_fma_f32 v[86:87], v[198:199], v[134:135], v[86:87] op_sel_hi:[0,1,1]
	v_pk_fma_f32 v[104:105], v[202:203], v[134:135], v[104:105] op_sel_hi:[0,1,1]
	v_pk_fma_f32 v[120:121], v[206:207], v[134:135], v[120:121] op_sel_hi:[0,1,1]
	v_pk_fma_f32 v[72:73], v[194:195], v[136:137], v[72:73] op_sel_hi:[0,1,1]
	v_pk_fma_f32 v[88:89], v[198:199], v[136:137], v[88:89] op_sel_hi:[0,1,1]
	v_pk_fma_f32 v[106:107], v[202:203], v[136:137], v[106:107] op_sel_hi:[0,1,1]
	v_pk_fma_f32 v[122:123], v[206:207], v[136:137], v[122:123] op_sel_hi:[0,1,1]
	s_waitcnt lgkmcnt(5)
	v_pk_fma_f32 v[74:75], v[194:195], v[138:139], v[74:75] op_sel_hi:[0,1,1]
	v_pk_fma_f32 v[90:91], v[198:199], v[138:139], v[90:91] op_sel_hi:[0,1,1]
	v_pk_fma_f32 v[108:109], v[202:203], v[138:139], v[108:109] op_sel_hi:[0,1,1]
	v_pk_fma_f32 v[24:25], v[206:207], v[138:139], v[24:25] op_sel_hi:[0,1,1]
	v_pk_fma_f32 v[76:77], v[194:195], v[140:141], v[76:77] op_sel_hi:[0,1,1]
	v_pk_fma_f32 v[94:95], v[198:199], v[140:141], v[94:95] op_sel_hi:[0,1,1]
	v_pk_fma_f32 v[110:111], v[202:203], v[140:141], v[110:111] op_sel_hi:[0,1,1]
	v_pk_fma_f32 v[26:27], v[206:207], v[140:141], v[26:27] op_sel_hi:[0,1,1]
	s_waitcnt lgkmcnt(4)
	v_pk_fma_f32 v[78:79], v[194:195], v[142:143], v[78:79] op_sel_hi:[0,1,1]
	v_pk_fma_f32 v[96:97], v[198:199], v[142:143], v[96:97] op_sel_hi:[0,1,1]
	v_pk_fma_f32 v[112:113], v[202:203], v[142:143], v[112:113] op_sel_hi:[0,1,1]
	v_pk_fma_f32 v[28:29], v[206:207], v[142:143], v[28:29] op_sel_hi:[0,1,1]
	v_pk_fma_f32 v[80:81], v[194:195], v[144:145], v[80:81] op_sel_hi:[0,1,1]
	v_pk_fma_f32 v[98:99], v[198:199], v[144:145], v[98:99] op_sel_hi:[0,1,1]
	v_pk_fma_f32 v[114:115], v[202:203], v[144:145], v[114:115] op_sel_hi:[0,1,1]
	v_pk_fma_f32 v[30:31], v[206:207], v[144:145], v[30:31] op_sel_hi:[0,1,1]
	s_waitcnt lgkmcnt(3)
	v_pk_fma_f32 v[66:67], v[194:195], v[146:147], v[66:67] op_sel:[1,0,0]
	v_pk_fma_f32 v[82:83], v[198:199], v[146:147], v[82:83] op_sel:[1,0,0]
	v_pk_fma_f32 v[100:101], v[202:203], v[146:147], v[100:101] op_sel:[1,0,0]
	v_pk_fma_f32 v[116:117], v[206:207], v[146:147], v[116:117] op_sel:[1,0,0]
	v_pk_fma_f32 v[68:69], v[194:195], v[148:149], v[68:69] op_sel:[1,0,0]
	v_pk_fma_f32 v[84:85], v[198:199], v[148:149], v[84:85] op_sel:[1,0,0]
	v_pk_fma_f32 v[102:103], v[202:203], v[148:149], v[102:103] op_sel:[1,0,0]
	v_pk_fma_f32 v[118:119], v[206:207], v[148:149], v[118:119] op_sel:[1,0,0]
	s_waitcnt lgkmcnt(2)
	v_pk_fma_f32 v[70:71], v[194:195], v[150:151], v[70:71] op_sel:[1,0,0]
	v_pk_fma_f32 v[86:87], v[198:199], v[150:151], v[86:87] op_sel:[1,0,0]
	v_pk_fma_f32 v[104:105], v[202:203], v[150:151], v[104:105] op_sel:[1,0,0]
	v_pk_fma_f32 v[120:121], v[206:207], v[150:151], v[120:121] op_sel:[1,0,0]
	v_pk_fma_f32 v[72:73], v[194:195], v[152:153], v[72:73] op_sel:[1,0,0]
	v_pk_fma_f32 v[88:89], v[198:199], v[152:153], v[88:89] op_sel:[1,0,0]
	v_pk_fma_f32 v[106:107], v[202:203], v[152:153], v[106:107] op_sel:[1,0,0]
	v_pk_fma_f32 v[122:123], v[206:207], v[152:153], v[122:123] op_sel:[1,0,0]
	s_waitcnt lgkmcnt(1)
	v_pk_fma_f32 v[74:75], v[194:195], v[154:155], v[74:75] op_sel:[1,0,0]
	v_pk_fma_f32 v[90:91], v[198:199], v[154:155], v[90:91] op_sel:[1,0,0]
	v_pk_fma_f32 v[108:109], v[202:203], v[154:155], v[108:109] op_sel:[1,0,0]
	v_pk_fma_f32 v[24:25], v[206:207], v[154:155], v[24:25] op_sel:[1,0,0]
	v_pk_fma_f32 v[76:77], v[194:195], v[156:157], v[76:77] op_sel:[1,0,0]
	v_pk_fma_f32 v[94:95], v[198:199], v[156:157], v[94:95] op_sel:[1,0,0]
	v_pk_fma_f32 v[110:111], v[202:203], v[156:157], v[110:111] op_sel:[1,0,0]
	v_pk_fma_f32 v[26:27], v[206:207], v[156:157], v[26:27] op_sel:[1,0,0]
	s_waitcnt lgkmcnt(0)
	v_pk_fma_f32 v[78:79], v[194:195], v[44:45], v[78:79] op_sel:[1,0,0]
	v_pk_fma_f32 v[96:97], v[198:199], v[44:45], v[96:97] op_sel:[1,0,0]
	v_pk_fma_f32 v[112:113], v[202:203], v[44:45], v[112:113] op_sel:[1,0,0]
	v_pk_fma_f32 v[28:29], v[206:207], v[44:45], v[28:29] op_sel:[1,0,0]
	v_pk_fma_f32 v[80:81], v[194:195], v[46:47], v[80:81] op_sel:[1,0,0]
	v_pk_fma_f32 v[98:99], v[198:199], v[46:47], v[98:99] op_sel:[1,0,0]
	v_pk_fma_f32 v[114:115], v[202:203], v[46:47], v[114:115] op_sel:[1,0,0]
	v_pk_fma_f32 v[30:31], v[206:207], v[46:47], v[30:31] op_sel:[1,0,0]
	s_waitcnt lgkmcnt(0)
	ds_bpermute_b32 v160, v48, v240
	ds_bpermute_b32 v161, v48, v241
	ds_bpermute_b32 v162, v48, v242
	ds_bpermute_b32 v163, v48, v243
	s_waitcnt lgkmcnt(0)
	v_add_f32_e32 v240, v240, v160
	v_add_f32_e32 v241, v241, v161
	v_add_f32_e32 v242, v242, v162
	v_add_f32_e32 v243, v243, v163
	ds_bpermute_b32 v160, v49, v240
	ds_bpermute_b32 v161, v49, v241
	ds_bpermute_b32 v162, v49, v242
	ds_bpermute_b32 v163, v49, v243
	s_waitcnt lgkmcnt(0)
	v_add_f32_e32 v240, v240, v160
	v_add_f32_e32 v241, v241, v161
	v_add_f32_e32 v242, v242, v162
	v_add_f32_e32 v243, v243, v163
	ds_bpermute_b32 v160, v50, v240
	ds_bpermute_b32 v161, v50, v241
	ds_bpermute_b32 v162, v50, v242
	ds_bpermute_b32 v163, v50, v243
	s_waitcnt lgkmcnt(0)
	v_add_f32_e32 v240, v240, v160
	v_add_f32_e32 v241, v241, v161
	v_add_f32_e32 v242, v242, v162
	v_add_f32_e32 v243, v243, v163
	ds_bpermute_b32 v160, v51, v240
	ds_bpermute_b32 v161, v51, v241
	ds_bpermute_b32 v162, v51, v242
	ds_bpermute_b32 v163, v51, v243
	s_waitcnt lgkmcnt(0)
	v_add_f32_e32 v240, v240, v160
	v_add_f32_e32 v241, v241, v161
	v_add_f32_e32 v242, v242, v162
	v_add_f32_e32 v243, v243, v163
	ds_bpermute_b32 v160, v52, v240
	ds_bpermute_b32 v161, v52, v241
	ds_bpermute_b32 v162, v52, v242
	ds_bpermute_b32 v163, v52, v243
	s_waitcnt lgkmcnt(0)
	v_add_f32_e32 v240, v240, v160
	v_add_f32_e32 v241, v241, v161
	v_add_f32_e32 v242, v242, v162
	v_add_f32_e32 v243, v243, v163
	ds_bpermute_b32 v160, v53, v240
	ds_bpermute_b32 v161, v53, v241
	ds_bpermute_b32 v162, v53, v242
	ds_bpermute_b32 v163, v53, v243
	s_waitcnt lgkmcnt(0)
	v_add_f32_e32 v240, v240, v160
	v_add_f32_e32 v241, v241, v161
	v_add_f32_e32 v242, v242, v162
	v_add_f32_e32 v243, v243, v163
	v_cndmask_b32_e32 v164, v74, v66, vcc
	v_cndmask_b32_e32 v196, v66, v74, vcc
	ds_bpermute_b32 v196, v53, v196
	v_cndmask_b32_e32 v165, v75, v67, vcc
	v_cndmask_b32_e32 v197, v67, v75, vcc
	ds_bpermute_b32 v197, v53, v197
	v_cndmask_b32_e32 v166, v76, v68, vcc
	v_cndmask_b32_e32 v198, v68, v76, vcc
	ds_bpermute_b32 v198, v53, v198
	v_cndmask_b32_e32 v167, v77, v69, vcc
	v_cndmask_b32_e32 v199, v69, v77, vcc
	ds_bpermute_b32 v199, v53, v199
	v_cndmask_b32_e32 v168, v78, v70, vcc
	v_cndmask_b32_e32 v200, v70, v78, vcc
	ds_bpermute_b32 v200, v53, v200
	v_cndmask_b32_e32 v169, v79, v71, vcc
	v_cndmask_b32_e32 v201, v71, v79, vcc
	ds_bpermute_b32 v201, v53, v201
	v_cndmask_b32_e32 v170, v80, v72, vcc
	v_cndmask_b32_e32 v202, v72, v80, vcc
	ds_bpermute_b32 v202, v53, v202
	v_cndmask_b32_e32 v171, v81, v73, vcc
	v_cndmask_b32_e32 v203, v73, v81, vcc
	ds_bpermute_b32 v203, v53, v203
	v_cndmask_b32_e32 v172, v90, v82, vcc
	v_cndmask_b32_e32 v204, v82, v90, vcc
	ds_bpermute_b32 v204, v53, v204
	v_cndmask_b32_e32 v173, v91, v83, vcc
	v_cndmask_b32_e32 v205, v83, v91, vcc
	ds_bpermute_b32 v205, v53, v205
	v_cndmask_b32_e32 v174, v94, v84, vcc
	v_cndmask_b32_e32 v206, v84, v94, vcc
	ds_bpermute_b32 v206, v53, v206
	v_cndmask_b32_e32 v175, v95, v85, vcc
	v_cndmask_b32_e32 v207, v85, v95, vcc
	ds_bpermute_b32 v207, v53, v207
	v_cndmask_b32_e32 v176, v96, v86, vcc
	v_cndmask_b32_e32 v208, v86, v96, vcc
	ds_bpermute_b32 v208, v53, v208
	v_cndmask_b32_e32 v177, v97, v87, vcc
	v_cndmask_b32_e32 v209, v87, v97, vcc
	ds_bpermute_b32 v209, v53, v209
	v_cndmask_b32_e32 v178, v98, v88, vcc
	v_cndmask_b32_e32 v210, v88, v98, vcc
	ds_bpermute_b32 v210, v53, v210
	v_cndmask_b32_e32 v179, v99, v89, vcc
	v_cndmask_b32_e32 v211, v89, v99, vcc
	ds_bpermute_b32 v211, v53, v211
	v_cndmask_b32_e32 v180, v108, v100, vcc
	v_cndmask_b32_e32 v212, v100, v108, vcc
	ds_bpermute_b32 v212, v53, v212
	v_cndmask_b32_e32 v181, v109, v101, vcc
	v_cndmask_b32_e32 v213, v101, v109, vcc
	ds_bpermute_b32 v213, v53, v213
	v_cndmask_b32_e32 v182, v110, v102, vcc
	v_cndmask_b32_e32 v214, v102, v110, vcc
	ds_bpermute_b32 v214, v53, v214
	v_cndmask_b32_e32 v183, v111, v103, vcc
	v_cndmask_b32_e32 v215, v103, v111, vcc
	ds_bpermute_b32 v215, v53, v215
	v_cndmask_b32_e32 v184, v112, v104, vcc
	v_cndmask_b32_e32 v216, v104, v112, vcc
	ds_bpermute_b32 v216, v53, v216
	v_cndmask_b32_e32 v185, v113, v105, vcc
	v_cndmask_b32_e32 v217, v105, v113, vcc
	ds_bpermute_b32 v217, v53, v217
	v_cndmask_b32_e32 v186, v114, v106, vcc
	v_cndmask_b32_e32 v218, v106, v114, vcc
	ds_bpermute_b32 v218, v53, v218
	v_cndmask_b32_e32 v187, v115, v107, vcc
	v_cndmask_b32_e32 v219, v107, v115, vcc
	ds_bpermute_b32 v219, v53, v219
	v_cndmask_b32_e32 v188, v24, v116, vcc
	v_cndmask_b32_e32 v220, v116, v24, vcc
	ds_bpermute_b32 v220, v53, v220
	v_cndmask_b32_e32 v189, v25, v117, vcc
	v_cndmask_b32_e32 v221, v117, v25, vcc
	ds_bpermute_b32 v221, v53, v221
	v_cndmask_b32_e32 v190, v26, v118, vcc
	v_cndmask_b32_e32 v222, v118, v26, vcc
	ds_bpermute_b32 v222, v53, v222
	v_cndmask_b32_e32 v191, v27, v119, vcc
	v_cndmask_b32_e32 v223, v119, v27, vcc
	ds_bpermute_b32 v223, v53, v223
	v_cndmask_b32_e32 v192, v28, v120, vcc
	v_cndmask_b32_e32 v224, v120, v28, vcc
	ds_bpermute_b32 v224, v53, v224
	v_cndmask_b32_e32 v193, v29, v121, vcc
	v_cndmask_b32_e32 v225, v121, v29, vcc
	ds_bpermute_b32 v225, v53, v225
	v_cndmask_b32_e32 v194, v30, v122, vcc
	v_cndmask_b32_e32 v226, v122, v30, vcc
	ds_bpermute_b32 v226, v53, v226
	v_cndmask_b32_e32 v195, v31, v123, vcc
	v_cndmask_b32_e32 v227, v123, v31, vcc
	ds_bpermute_b32 v227, v53, v227
	s_waitcnt lgkmcnt(0)
	v_add_f32_e32 v164, v164, v196
	v_add_f32_e32 v165, v165, v197
	v_add_f32_e32 v166, v166, v198
	v_add_f32_e32 v167, v167, v199
	v_add_f32_e32 v168, v168, v200
	v_add_f32_e32 v169, v169, v201
	v_add_f32_e32 v170, v170, v202
	v_add_f32_e32 v171, v171, v203
	v_add_f32_e32 v172, v172, v204
	v_add_f32_e32 v173, v173, v205
	v_add_f32_e32 v174, v174, v206
	v_add_f32_e32 v175, v175, v207
	v_add_f32_e32 v176, v176, v208
	v_add_f32_e32 v177, v177, v209
	v_add_f32_e32 v178, v178, v210
	v_add_f32_e32 v179, v179, v211
	v_add_f32_e32 v180, v180, v212
	v_add_f32_e32 v181, v181, v213
	v_add_f32_e32 v182, v182, v214
	v_add_f32_e32 v183, v183, v215
	v_add_f32_e32 v184, v184, v216
	v_add_f32_e32 v185, v185, v217
	v_add_f32_e32 v186, v186, v218
	v_add_f32_e32 v187, v187, v219
	v_add_f32_e32 v188, v188, v220
	v_add_f32_e32 v189, v189, v221
	v_add_f32_e32 v190, v190, v222
	v_add_f32_e32 v191, v191, v223
	v_add_f32_e32 v192, v192, v224
	v_add_f32_e32 v193, v193, v225
	v_add_f32_e32 v194, v194, v226
	v_add_f32_e32 v195, v195, v227
	v_cndmask_b32_e64 v228, v168, v164, s[0:1]
	v_cndmask_b32_e64 v142, v164, v168, s[0:1]
	ds_bpermute_b32 v142, v52, v142
	v_cndmask_b32_e64 v229, v169, v165, s[0:1]
	v_cndmask_b32_e64 v143, v165, v169, s[0:1]
	ds_bpermute_b32 v143, v52, v143
	v_cndmask_b32_e64 v230, v170, v166, s[0:1]
	v_cndmask_b32_e64 v144, v166, v170, s[0:1]
	ds_bpermute_b32 v144, v52, v144
	v_cndmask_b32_e64 v231, v171, v167, s[0:1]
	v_cndmask_b32_e64 v145, v167, v171, s[0:1]
	ds_bpermute_b32 v145, v52, v145
	v_cndmask_b32_e64 v130, v176, v172, s[0:1]
	v_cndmask_b32_e64 v146, v172, v176, s[0:1]
	ds_bpermute_b32 v146, v52, v146
	v_cndmask_b32_e64 v131, v177, v173, s[0:1]
	v_cndmask_b32_e64 v147, v173, v177, s[0:1]
	ds_bpermute_b32 v147, v52, v147
	v_cndmask_b32_e64 v132, v178, v174, s[0:1]
	v_cndmask_b32_e64 v148, v174, v178, s[0:1]
	ds_bpermute_b32 v148, v52, v148
	v_cndmask_b32_e64 v133, v179, v175, s[0:1]
	v_cndmask_b32_e64 v149, v175, v179, s[0:1]
	ds_bpermute_b32 v149, v52, v149
	v_cndmask_b32_e64 v134, v184, v180, s[0:1]
	v_cndmask_b32_e64 v150, v180, v184, s[0:1]
	ds_bpermute_b32 v150, v52, v150
	v_cndmask_b32_e64 v135, v185, v181, s[0:1]
	v_cndmask_b32_e64 v151, v181, v185, s[0:1]
	ds_bpermute_b32 v151, v52, v151
	v_cndmask_b32_e64 v136, v186, v182, s[0:1]
	v_cndmask_b32_e64 v152, v182, v186, s[0:1]
	ds_bpermute_b32 v152, v52, v152
	v_cndmask_b32_e64 v137, v187, v183, s[0:1]
	v_cndmask_b32_e64 v153, v183, v187, s[0:1]
	ds_bpermute_b32 v153, v52, v153
	v_cndmask_b32_e64 v138, v192, v188, s[0:1]
	v_cndmask_b32_e64 v154, v188, v192, s[0:1]
	ds_bpermute_b32 v154, v52, v154
	v_cndmask_b32_e64 v139, v193, v189, s[0:1]
	v_cndmask_b32_e64 v155, v189, v193, s[0:1]
	ds_bpermute_b32 v155, v52, v155
	v_cndmask_b32_e64 v140, v194, v190, s[0:1]
	v_cndmask_b32_e64 v156, v190, v194, s[0:1]
	ds_bpermute_b32 v156, v52, v156
	v_cndmask_b32_e64 v141, v195, v191, s[0:1]
	v_cndmask_b32_e64 v157, v191, v195, s[0:1]
	ds_bpermute_b32 v157, v52, v157
	s_waitcnt lgkmcnt(0)
	v_add_f32_e32 v228, v228, v142
	v_add_f32_e32 v229, v229, v143
	v_add_f32_e32 v230, v230, v144
	v_add_f32_e32 v231, v231, v145
	v_add_f32_e32 v130, v130, v146
	v_add_f32_e32 v131, v131, v147
	v_add_f32_e32 v132, v132, v148
	v_add_f32_e32 v133, v133, v149
	v_add_f32_e32 v134, v134, v150
	v_add_f32_e32 v135, v135, v151
	v_add_f32_e32 v136, v136, v152
	v_add_f32_e32 v137, v137, v153
	v_add_f32_e32 v138, v138, v154
	v_add_f32_e32 v139, v139, v155
	v_add_f32_e32 v140, v140, v156
	v_add_f32_e32 v141, v141, v157
	v_cndmask_b32_e64 v44, v230, v228, s[2:3]
	v_cndmask_b32_e64 v200, v228, v230, s[2:3]
	ds_bpermute_b32 v200, v51, v200
	v_cndmask_b32_e64 v45, v231, v229, s[2:3]
	v_cndmask_b32_e64 v201, v229, v231, s[2:3]
	ds_bpermute_b32 v201, v51, v201
	v_cndmask_b32_e64 v46, v132, v130, s[2:3]
	v_cndmask_b32_e64 v202, v130, v132, s[2:3]
	ds_bpermute_b32 v202, v51, v202
	v_cndmask_b32_e64 v47, v133, v131, s[2:3]
	v_cndmask_b32_e64 v203, v131, v133, s[2:3]
	ds_bpermute_b32 v203, v51, v203
	v_cndmask_b32_e64 v196, v136, v134, s[2:3]
	v_cndmask_b32_e64 v204, v134, v136, s[2:3]
	ds_bpermute_b32 v204, v51, v204
	v_cndmask_b32_e64 v197, v137, v135, s[2:3]
	v_cndmask_b32_e64 v205, v135, v137, s[2:3]
	ds_bpermute_b32 v205, v51, v205
	v_cndmask_b32_e64 v198, v140, v138, s[2:3]
	v_cndmask_b32_e64 v206, v138, v140, s[2:3]
	ds_bpermute_b32 v206, v51, v206
	v_cndmask_b32_e64 v199, v141, v139, s[2:3]
	v_cndmask_b32_e64 v207, v139, v141, s[2:3]
	ds_bpermute_b32 v207, v51, v207
	s_waitcnt lgkmcnt(0)
	v_add_f32_e32 v44, v44, v200
	v_add_f32_e32 v45, v45, v201
	v_add_f32_e32 v46, v46, v202
	v_add_f32_e32 v47, v47, v203
	v_add_f32_e32 v196, v196, v204
	v_add_f32_e32 v197, v197, v205
	v_add_f32_e32 v198, v198, v206
	v_add_f32_e32 v199, v199, v207
	v_cndmask_b32_e64 v208, v45, v44, s[4:5]
	v_cndmask_b32_e64 v212, v44, v45, s[4:5]
	ds_bpermute_b32 v212, v50, v212
	v_cndmask_b32_e64 v209, v47, v46, s[4:5]
	v_cndmask_b32_e64 v213, v46, v47, s[4:5]
	ds_bpermute_b32 v213, v50, v213
	v_cndmask_b32_e64 v210, v197, v196, s[4:5]
	v_cndmask_b32_e64 v214, v196, v197, s[4:5]
	ds_bpermute_b32 v214, v50, v214
	v_cndmask_b32_e64 v211, v199, v198, s[4:5]
	v_cndmask_b32_e64 v215, v198, v199, s[4:5]
	ds_bpermute_b32 v215, v50, v215
	s_waitcnt lgkmcnt(0)
	v_add_f32_e32 v208, v208, v212
	v_add_f32_e32 v209, v209, v213
	v_add_f32_e32 v210, v210, v214
	v_add_f32_e32 v211, v211, v215
	ds_bpermute_b32 v216, v49, v208
	ds_bpermute_b32 v217, v49, v209
	ds_bpermute_b32 v218, v49, v210
	ds_bpermute_b32 v219, v49, v211
	s_waitcnt lgkmcnt(0)
	v_add_f32_e32 v208, v208, v216
	v_add_f32_e32 v209, v209, v217
	v_add_f32_e32 v210, v210, v218
	v_add_f32_e32 v211, v211, v219
	ds_bpermute_b32 v216, v48, v208
	ds_bpermute_b32 v217, v48, v209
	ds_bpermute_b32 v218, v48, v210
	ds_bpermute_b32 v219, v48, v211
	s_waitcnt lgkmcnt(0)
	v_add_f32_e32 v208, v208, v216
	v_add_f32_e32 v209, v209, v217
	v_add_f32_e32 v210, v210, v218
	v_add_f32_e32 v211, v211, v219
	v_fmamk_f32 v224, v240, 0x3a000000, v125
	v_cmp_gt_f32_e64 s[10:11], s13, v224
	v_mul_f32_e32 v225, 0x4b800000, v224
	s_nop 0
	v_cndmask_b32_e64 v225, v224, v225, s[10:11]
	v_rsq_f32_e32 v224, v225
	s_nop 1
	v_mul_f32_e32 v225, 0x45800000, v224
	v_cndmask_b32_e64 v220, v224, v225, s[10:11]
	v_fmamk_f32 v224, v241, 0x3a000000, v125
	v_cmp_gt_f32_e64 s[10:11], s13, v224
	v_mul_f32_e32 v225, 0x4b800000, v224
	s_nop 0
	v_cndmask_b32_e64 v225, v224, v225, s[10:11]
	v_rsq_f32_e32 v224, v225
	s_nop 1
	v_mul_f32_e32 v225, 0x45800000, v224
	v_cndmask_b32_e64 v221, v224, v225, s[10:11]
	v_fmamk_f32 v224, v242, 0x3a000000, v125
	v_cmp_gt_f32_e64 s[10:11], s13, v224
	v_mul_f32_e32 v225, 0x4b800000, v224
	s_nop 0
	v_cndmask_b32_e64 v225, v224, v225, s[10:11]
	v_rsq_f32_e32 v224, v225
	s_nop 1
	v_mul_f32_e32 v225, 0x45800000, v224
	v_cndmask_b32_e64 v222, v224, v225, s[10:11]
	v_fmamk_f32 v224, v243, 0x3a000000, v125
	v_cmp_gt_f32_e64 s[10:11], s13, v224
	v_mul_f32_e32 v225, 0x4b800000, v224
	s_nop 0
	v_cndmask_b32_e64 v225, v224, v225, s[10:11]
	v_rsq_f32_e32 v224, v225
	s_nop 1
	v_mul_f32_e32 v225, 0x45800000, v224
	v_cndmask_b32_e64 v223, v224, v225, s[10:11]
	v_and_b32_e32 v224, 1, v93
	v_cmp_ne_u32_e64 s[24:25], 0, v224
	v_and_b32_e32 v225, 2, v93
	v_cmp_ne_u32_e64 s[26:27], 0, v225
	s_nop 1
	v_cndmask_b32_e64 v226, v208, v209, s[24:25]
	v_cndmask_b32_e64 v142, v210, v211, s[24:25]
	v_cndmask_b32_e64 v226, v226, v142, s[26:27]
	v_cndmask_b32_e64 v227, v220, v221, s[24:25]
	v_cndmask_b32_e64 v142, v222, v223, s[24:25]
	v_cndmask_b32_e64 v227, v227, v142, s[26:27]
	s_waitcnt vmcnt(63)
	v_mov_b32_e32 v1, v253
	v_fmac_f32_e32 v1, v227, v226
	v_cmp_nlt_f32_e64 s[10:11], s31, v1
	s_and_saveexec_b64 s[28:29], s[10:11]
	s_cbranch_execz .Lmy_partb4_sp
	v_mul_f32_e32 v2, 0x3fb8aa3b, v1
	v_rndne_f32_e32 v3, v2
	v_sub_f32_e32 v4, v2, v3
	v_fma_f32 v2, v1, s34, -v2
	v_fmac_f32_e32 v2, 0x32a5705f, v1
	v_add_f32_e32 v2, v4, v2
	v_cvt_i32_f32_e32 v3, v3
	v_exp_f32_e32 v2, v2
	v_cmp_ngt_f32_e64 s[10:11], s35, v1
	v_ldexp_f32 v2, v2, v3
	s_nop 0
	v_cndmask_b32_e64 v2, 0, v2, s[10:11]
	v_cmp_nlt_f32_e64 s[10:11], s36, v1
	s_nop 1
	v_cndmask_b32_e64 v1, v127, v2, s[10:11]
	v_add_f32_e32 v4, 1.0, v1
	v_add_f32_e32 v2, -1.0, v4
	v_sub_f32_e32 v3, v2, v4
	v_add_f32_e32 v3, 1.0, v3
	v_sub_f32_e32 v2, v1, v2
	v_add_f32_e32 v5, v2, v3
	v_frexp_mant_f32_e32 v6, v4
	v_cvt_f64_f32_e32 v[2:3], v4
	v_frexp_exp_i32_f64_e32 v2, v[2:3]
	v_cmp_gt_f32_e64 s[10:11], s38, v6
	s_nop 1
	v_subbrev_co_u32_e64 v10, s[10:11], 0, v2, s[10:11]
	v_sub_u32_e32 v2, 0, v10
	v_ldexp_f32 v3, v4, v2
	v_add_f32_e32 v4, -1.0, v3
	v_add_f32_e32 v6, 1.0, v3
	v_ldexp_f32 v2, v5, v2
	v_add_f32_e32 v5, 1.0, v4
	v_add_f32_e32 v7, -1.0, v6
	v_sub_f32_e32 v5, v3, v5
	v_sub_f32_e32 v3, v3, v7
	v_add_f32_e32 v5, v2, v5
	v_add_f32_e32 v2, v2, v3
	v_add_f32_e32 v11, v6, v2
	v_rcp_f32_e32 v13, v11
	v_sub_f32_e32 v3, v6, v11
	v_add_f32_e32 v12, v2, v3
	v_add_f32_e32 v3, v4, v5
	v_mul_f32_e32 v15, v3, v13
	v_sub_f32_e32 v2, v4, v3
	v_mul_f32_e32 v4, v11, v15
	v_fma_f32 v6, v15, v11, -v4
	v_fmac_f32_e32 v6, v15, v12
	v_add_f32_e32 v14, v5, v2
	v_add_f32_e32 v2, v4, v6
	v_sub_f32_e32 v5, v3, v2
	v_pk_add_f32 v[8:9], v[2:3], v[4:5] neg_lo:[0,1] neg_hi:[0,1]
	v_mov_b32_e32 v7, v2
	v_pk_add_f32 v[2:3], v[8:9], v[6:7] neg_lo:[0,1] neg_hi:[0,1]
	v_cmp_neq_f32_e64 s[10:11], s37, v1
	v_add_f32_e32 v3, v14, v3
	v_add_f32_e32 v2, v2, v3
	v_add_f32_e32 v3, v5, v2
	v_mul_f32_e32 v14, v13, v3
	v_mul_f32_e32 v4, v11, v14
	v_fma_f32 v6, v14, v11, -v4
	v_fmac_f32_e32 v6, v14, v12
	v_sub_f32_e32 v5, v5, v3
	v_add_f32_e32 v11, v2, v5
	v_add_f32_e32 v2, v4, v6
	v_sub_f32_e32 v5, v3, v2
	v_pk_add_f32 v[8:9], v[2:3], v[4:5] neg_lo:[0,1] neg_hi:[0,1]
	v_mov_b32_e32 v7, v2
	v_pk_add_f32 v[2:3], v[8:9], v[6:7] neg_lo:[0,1] neg_hi:[0,1]
	s_nop 0
	v_add_f32_e32 v3, v11, v3
	v_add_f32_e32 v2, v2, v3
	v_add_f32_e32 v3, v15, v14
	v_add_f32_e32 v2, v5, v2
	v_sub_f32_e32 v4, v3, v15
	v_mul_f32_e32 v2, v13, v2
	v_sub_f32_e32 v4, v14, v4
	v_add_f32_e32 v4, v4, v2
	v_add_f32_e32 v6, v3, v4
	v_mul_f32_e32 v7, v6, v6
	v_fmamk_f32 v2, v7, 0x3e9b6dac, v126
	v_fmaak_f32 v43, v7, v2, 0x3f2aaada
	v_cvt_f32_i32_e32 v2, v10
	v_sub_f32_e32 v3, v6, v3
	v_sub_f32_e32 v3, v4, v3
	v_ldexp_f32 v8, v3, 1
	v_mul_f32_e32 v3, v6, v7
	v_ldexp_f32 v5, v6, 1
	v_pk_mul_f32 v[6:7], v[2:3], v[42:43]
	s_nop 0
	v_fma_f32 v4, v2, s39, -v6
	v_fmac_f32_e32 v4, 0xb102e308, v2
	v_pk_add_f32 v[2:3], v[6:7], v[4:5]
	s_nop 0
	v_sub_f32_e32 v5, v3, v5
	v_sub_f32_e32 v5, v7, v5
	v_add_f32_e32 v9, v8, v5
	v_mov_b32_e32 v8, v6
	v_pk_add_f32 v[6:7], v[2:3], v[6:7] neg_lo:[0,1] neg_hi:[0,1]
	v_pk_add_f32 v[10:11], v[2:3], v[8:9]
	v_mov_b32_e32 v5, v2
	v_mov_b32_e32 v7, v11
	v_pk_add_f32 v[12:13], v[4:5], v[6:7] neg_lo:[0,1] neg_hi:[0,1]
	v_pk_add_f32 v[4:5], v[4:5], v[6:7]
	v_mov_b32_e32 v8, v9
	v_pk_add_f32 v[6:7], v[4:5], v[2:3] op_sel:[1,0] op_sel_hi:[0,1] neg_lo:[0,1] neg_hi:[0,1]
	v_pk_add_f32 v[14:15], v[10:11], v[6:7] op_sel_hi:[1,0] neg_lo:[0,1] neg_hi:[0,1]
	v_mov_b32_e32 v10, v11
	v_mov_b32_e32 v11, v5
	v_pk_mov_b32 v[6:7], v[2:3], v[6:7] op_sel:[1,0]
	v_mov_b32_e32 v9, v2
	v_pk_add_f32 v[6:7], v[10:11], v[6:7] neg_lo:[0,1] neg_hi:[0,1]
	v_mov_b32_e32 v14, v12
	v_pk_add_f32 v[2:3], v[8:9], v[6:7] neg_lo:[0,1] neg_hi:[0,1]
	v_mov_b32_e32 v13, v5
	v_pk_add_f32 v[6:7], v[14:15], v[2:3]
	s_nop 0
	v_pk_add_f32 v[8:9], v[6:7], v[6:7] op_sel:[0,1] op_sel_hi:[1,0]
	s_nop 0
	v_pk_add_f32 v[4:5], v[4:5], v[8:9] op_sel:[1,0] op_sel_hi:[0,1]
	v_mov_b32_e32 v7, v4
	v_pk_add_f32 v[10:11], v[6:7], v[12:13] neg_lo:[0,1] neg_hi:[0,1]
	v_mov_b32_e32 v3, v8
	v_sub_f32_e32 v5, v6, v10
	v_pk_add_f32 v[2:3], v[2:3], v[10:11] neg_lo:[0,1] neg_hi:[0,1]
	v_sub_f32_e32 v5, v12, v5
	v_add_f32_e32 v2, v2, v5
	v_add_f32_e32 v2, v2, v3
	v_add_f32_e32 v2, v4, v2
	v_cndmask_b32_e64 v2, v127, v2, s[10:11]
	v_cmp_lt_f32_e64 s[10:11], |v1|, s40
	s_nop 1
	v_cndmask_b32_e64 v1, v2, v1, s[10:11]
.Lmy_partb4_sp:
	s_or_b64 exec, exec, s[28:29]
	v_and_b32_e32 v144, 3, v93
	v_mov_b32_e32 v145, 0
	v_lshlrev_b32_e32 v146, 17, v144
	v_mov_b32_e32 v147, 0
	v_lshl_add_u64 v[146:147], v[36:37], 0, v[146:147]
	v_lshl_add_u64 v[146:147], s[84:85], 0, v[146:147]
	global_store_dword v[146:147], v1, off
	v_lshlrev_b32_e32 v148, 13, v144
	v_mov_b32_e32 v149, 0
	v_lshl_add_u64 v[148:149], v[34:35], 0, v[148:149]
	v_lshl_add_u64 v[148:149], s[84:85], 0, v[148:149]
	v_cmp_gt_u32_e64 s[10:11], 4, v93
	s_and_saveexec_b64 s[28:29], s[10:11]
	global_store_dword v[148:149], v227, off
	s_or_b64 exec, exec, s[28:29]
